# adds: nt (streaming) cache policy on the QKV epilogue stores as well
# speedup vs baseline: 1.0124x; 1.0124x over previous
; __device__ __forceinline__ unsigned cvt_pk_bf16(float lo, float hi) { unsigned r; asm volatile("v_cvt_pk_bf16_f32 %0, %1, %2" : "=v"(r) : "v"(lo), "v"(hi)); return r; }
; DI float x16_sum(float x) { const unsigned u = __builtin_bit_cast(unsigned, x); auto r = __builtin_amdgcn_permlane16_swap(u, u, false, false); return __builtin_bit_cast(float, (unsigned)r[0]) + __builtin_bit_cast(float, (unsigned)r[1]); }
; DI float x32_sum(float x) { const unsigned u = __builtin_bit_cast(unsigned, x); auto r = __builtin_amdgcn_permlane32_swap(u, u, false, false); return __builtin_bit_cast(float, (unsigned)r[0]) + __builtin_bit_cast(float, (unsigned)r[1]); }
;     __device__ __forceinline__ void operator()(const f32x4 (&acc)[2][2][4][2], const Unit& u, int wr, int wc, int fr, int fq) const {
;     ...
; #pragma unroll
;             for (int ai = 0; ai < 2; ++ai)
; #pragma unroll
;                 for (int m = 0; m < 4; ++m) {
;                     const int r = row0 + ai * HALF + m * 16;
;                     const float rs = __builtin_amdgcn_rsqf((float)ss[r] * (1.0f / 1048576.0f) * (1.0f / 1024.0f) + EPS);
;                     f32x4 v[2][2]; float sq = 0.f;
; #pragma unroll
;                     for (int bj = 0; bj < 2; ++bj)
; #pragma unroll
;                         for (int n = 0; n < 2; ++n) { v[bj][n] = acc[ai][bj][m][n] * rs; sq += (v[bj][n][0] * v[bj][n][0] + v[bj][n][1] * v[bj][n][1]) + (v[bj][n][2] * v[bj][n][2] + v[bj][n][3] * v[bj][n][3]); }
;                     sq = x16_sum(sq); sq = x32_sum(sq);
;                     const float r2 = (sec < 2) ? qsc * __builtin_amdgcn_rsqf(sq * (1.0f / 64.0f) + EPS) : 1.0f;
;                     const int bl = r >> 13, t = r & 8191; const int pr = (bl << 13) + ((t & ((1 << dsh) - 1)) << (13 - dsh)) + (t >> dsh);
;                     bf16_t* rowp = O + (size_t)blk * SEC + (size_t)pr * 1024 + cin;
; #pragma unroll
;                     for (int bj = 0; bj < 2; ++bj) { const f32x4 v0 = v[bj][0] * gn[bj][0] * r2, v1 = v[bj][1] * gn[bj][1] * r2;
;                         u32x4 w; w.x = cvt_pk_bf16(v0[0], v0[1]); w.y = cvt_pk_bf16(v0[2], v0[3]); w.z = cvt_pk_bf16(v1[0], v1[1]); w.w = cvt_pk_bf16(v1[2], v1[3]);
;                         *(u32x4*)(rowp + bj * 32) = w; }
.LBB0_433:
	s_cmp_ge_u32 s88, 6
	s_cbranch_scc1 .Lv433
	s_mov_b32 vcc_lo, 0xff00ff00
	s_mov_b32 vcc_hi, 0xff00ff00
	s_nop 1
	v_lshl_add_u64 v[162:163], v[160:161], 3, s[48:49]
	s_cmp_eq_u32 s2, 1
	s_cselect_b32 s34, 2, 4
	s_cmp_lg_u32 s2, 0
	v_cndmask_b32_e64 v171, 1.0, v234, s[0:1]
	s_cselect_b32 s34, s34, 0
	s_sub_i32 s42, 13, s34
	s_and_b32 s43, s69, 0xffffe000
	s_ashr_i32 s89, s88, 31
	s_and_b32 s2, s76, 0x300
	s_lshl_b64 s[0:1], s[88:89], 25
	s_add_u32 s0, s28, s0
	v_or_b32_e32 v172, s2, v169
	s_addc_u32 s1, s29, s1
	s_movk_i32 s2, 0x1fdf
	s_mov_b32 s88, 0x1000
	s_cmp_eq_u32 s34, 0
	s_cselect_b32 s88, 0x4000, s88
	s_cmp_eq_u32 s34, 4
	s_cselect_b32 s88, 0x800000, s88
	s_lshr_b32 s89, 0x8000, s34
	v_mov_b32_e32 v220, s88
	v_mov_b32_e32 v176, s89
	s_mul_i32 s89, s89, 5
	v_mov_b32_e32 v177, 0
	v_sub_u32_e32 v218, 64, v220
	v_mov_b32_e32 v178, s89
	v_mov_b32_e32 v179, 0
	v_cndmask_b32_e64 v219, 0, -1, vcc
	v_cndmask_b32_e64 v218, 0, v218, vcc
	v_cndmask_b32_e64 v220, v220, 64, vcc
	v_mov_b32_e32 v221, 0
	s_waitcnt vmcnt(0)
	s_nop 1
	v_cvt_f32_u32_e32 v165, v193
	v_cvt_f32_u32_e32 v164, v192
	v_fmamk_f32 v164, v165, 0x4f800000, v164
	v_fmamk_f32 v164, v164, 0x30800000, v229
	v_rsq_f32_e32 v112, v164
	s_nop 0
	v_pk_mul_f32 v[144:145], v[144:145], v[112:113] op_sel_hi:[1,0]
	v_pk_mul_f32 v[222:223], v[144:145], v[144:145]
	v_pk_mul_f32 v[164:165], v[142:143], v[112:113] op_sel_hi:[1,0]
	v_pk_fma_f32 v[222:223], v[164:165], v[164:165], v[222:223]
	v_pk_mul_f32 v[140:141], v[140:141], v[112:113] op_sel_hi:[1,0]
	v_pk_fma_f32 v[222:223], v[140:141], v[140:141], v[222:223]
	v_pk_mul_f32 v[142:143], v[138:139], v[112:113] op_sel_hi:[1,0]
	v_pk_fma_f32 v[222:223], v[142:143], v[142:143], v[222:223]
	v_pk_mul_f32 v[136:137], v[136:137], v[112:113] op_sel_hi:[1,0]
	v_pk_fma_f32 v[222:223], v[136:137], v[136:137], v[222:223]
	v_pk_mul_f32 v[138:139], v[134:135], v[112:113] op_sel_hi:[1,0]
	v_pk_fma_f32 v[222:223], v[138:139], v[138:139], v[222:223]
	v_pk_mul_f32 v[132:133], v[132:133], v[112:113] op_sel_hi:[1,0]
	v_pk_fma_f32 v[222:223], v[132:133], v[132:133], v[222:223]
	v_pk_mul_f32 v[134:135], v[130:131], v[112:113] op_sel_hi:[1,0]
	v_pk_fma_f32 v[222:223], v[134:135], v[134:135], v[222:223]
	v_add_f32_e32 v112, v222, v223
	v_mov_b32_e32 v130, v112
	s_nop 1
	v_permlane16_swap_b32_e32 v112, v130
	v_add_f32_e32 v112, v112, v130
	v_mov_b32_e32 v130, v112
	s_nop 1
	v_permlane32_swap_b32_e32 v112, v130
	v_add_f32_e32 v112, v112, v130
	v_fmamk_f32 v112, v112, 0x3c800000, v229
	v_rsq_f32_e32 v112, v112
	v_lshlrev_b32_e32 v131, s42, v160
	v_and_b32_e32 v131, 0x1ffe, v131
	v_pk_mul_f32 v[164:165], v[92:93], v[164:165]
	v_mul_f32_e32 v112, v171, v112
	v_cndmask_b32_e64 v130, 1.0, v112, s[40:41]
	v_and_b32_e32 v112, 0x1fcf, v160
	v_lshrrev_b32_e32 v112, s34, v112
	v_or_b32_e32 v112, s43, v112
	v_add_u32_e32 v166, v112, v131
	v_ashrrev_i32_e32 v167, 31, v166
	v_lshlrev_b64 v[166:167], 11, v[166:167]
	v_lshl_add_u64 v[166:167], s[0:1], 0, v[166:167]
	v_lshlrev_b32_e32 v112, 1, v172
	v_pk_mul_f32 v[144:145], v[94:95], v[144:145]
	v_pk_mul_f32 v[142:143], v[88:89], v[142:143]
	v_pk_mul_f32 v[140:141], v[90:91], v[140:141]
	v_lshl_add_u64 v[166:167], v[166:167], 0, v[112:113]
	v_pk_mul_f32 v[144:145], v[144:145], v[130:131] op_sel_hi:[1,0]
	v_pk_mul_f32 v[164:165], v[164:165], v[130:131] op_sel_hi:[1,0]
	v_pk_mul_f32 v[172:173], v[140:141], v[130:131] op_sel_hi:[1,0]
	v_pk_mul_f32 v[142:143], v[142:143], v[130:131] op_sel_hi:[1,0]
	v_cvt_pk_bf16_f32 v184, v164, v165
	v_cvt_pk_bf16_f32 v185, v144, v145
	v_pk_mul_f32 v[134:135], v[80:81], v[134:135]
	v_pk_mul_f32 v[132:133], v[82:83], v[132:133]
	v_cvt_pk_bf16_f32 v186, v142, v143
	v_cvt_pk_bf16_f32 v187, v172, v173
	v_pk_mul_f32 v[138:139], v[84:85], v[138:139]
	v_pk_mul_f32 v[136:137], v[86:87], v[136:137]
	v_pk_mul_f32 v[140:141], v[132:133], v[130:131] op_sel_hi:[1,0]
	v_pk_mul_f32 v[132:133], v[134:135], v[130:131] op_sel_hi:[1,0]
	v_pk_mul_f32 v[136:137], v[136:137], v[130:131] op_sel_hi:[1,0]
	v_pk_mul_f32 v[138:139], v[138:139], v[130:131] op_sel_hi:[1,0]
	s_nop 0
	v_cvt_pk_bf16_f32 v130, v138, v139
	v_cvt_pk_bf16_f32 v131, v136, v137
	v_cvt_pk_bf16_f32 v132, v132, v133
	v_cvt_pk_bf16_f32 v133, v140, v141
	v_mov_b32_dpp v180, v184 row_ror:8 row_mask:0xf bank_mask:0xf
	v_mov_b32_dpp v181, v185 row_ror:8 row_mask:0xf bank_mask:0xf
	v_mov_b32_dpp v182, v186 row_ror:8 row_mask:0xf bank_mask:0xf
	v_mov_b32_dpp v183, v187 row_ror:8 row_mask:0xf bank_mask:0xf
	v_lshl_add_u64 v[212:213], v[166:167], 0, v[218:219]
	v_mov_b32_dpp v184, v130 row_ror:8 row_mask:0xf bank_mask:0xc
	v_mov_b32_dpp v185, v131 row_ror:8 row_mask:0xf bank_mask:0xc
	v_mov_b32_dpp v186, v132 row_ror:8 row_mask:0xf bank_mask:0xc
	v_mov_b32_dpp v187, v133 row_ror:8 row_mask:0xf bank_mask:0xc
	v_lshl_add_u64 v[214:215], v[166:167], 0, v[220:221]
	v_cndmask_b32_e32 v130, v180, v130, vcc
	v_cndmask_b32_e32 v131, v181, v131, vcc
	v_cndmask_b32_e32 v132, v182, v132, vcc
	v_cndmask_b32_e32 v133, v183, v133, vcc
	s_nop 0
	global_store_dwordx4 v[212:213], v[184:187], off nt
	global_store_dwordx4 v[214:215], v[130:133], off nt
	v_lshl_add_u64 v[174:175], v[166:167], 0, v[176:177]
	s_nop 1
	v_or_b32_e32 v133, 16, v160
	v_cvt_f32_u32_e32 v131, v195
	v_cvt_f32_u32_e32 v130, v194
	v_fmamk_f32 v130, v131, 0x4f800000, v130
	v_fmamk_f32 v130, v130, 0x30800000, v229
	v_rsq_f32_e32 v132, v130
	s_nop 0
	v_pk_mul_f32 v[128:129], v[128:129], v[132:133] op_sel_hi:[1,0]
	v_pk_mul_f32 v[222:223], v[128:129], v[128:129]
	v_pk_mul_f32 v[130:131], v[126:127], v[132:133] op_sel_hi:[1,0]
	v_pk_fma_f32 v[222:223], v[130:131], v[130:131], v[222:223]
; __device__ __forceinline__ unsigned cvt_pk_bf16(float lo, float hi) { unsigned r; asm volatile("v_cvt_pk_bf16_f32 %0, %1, %2" : "=v"(r) : "v"(lo), "v"(hi)); return r; }
; DI float x16_sum(float x) { const unsigned u = __builtin_bit_cast(unsigned, x); auto r = __builtin_amdgcn_permlane16_swap(u, u, false, false); return __builtin_bit_cast(float, (unsigned)r[0]) + __builtin_bit_cast(float, (unsigned)r[1]); }
; DI float x32_sum(float x) { const unsigned u = __builtin_bit_cast(unsigned, x); auto r = __builtin_amdgcn_permlane32_swap(u, u, false, false); return __builtin_bit_cast(float, (unsigned)r[0]) + __builtin_bit_cast(float, (unsigned)r[1]); }
;     __device__ __forceinline__ void operator()(const f32x4 (&acc)[2][2][4][2], const Unit& u, int wr, int wc, int fr, int fq) const {
;     ...
;                 for (int m = 0; m < 4; ++m) {
;                     const int r = row0 + ai * HALF + m * 16;
;                     const float rs = __builtin_amdgcn_rsqf((float)ss[r] * (1.0f / 1048576.0f) * (1.0f / 1024.0f) + EPS);
;                     f32x4 v[2][2]; float sq = 0.f;
; #pragma unroll
;                     for (int bj = 0; bj < 2; ++bj)
; #pragma unroll
;                         for (int n = 0; n < 2; ++n) { v[bj][n] = acc[ai][bj][m][n] * rs; sq += (v[bj][n][0] * v[bj][n][0] + v[bj][n][1] * v[bj][n][1]) + (v[bj][n][2] * v[bj][n][2] + v[bj][n][3] * v[bj][n][3]); }
;                     sq = x16_sum(sq); sq = x32_sum(sq);
;                     const float r2 = (sec < 2) ? qsc * __builtin_amdgcn_rsqf(sq * (1.0f / 64.0f) + EPS) : 1.0f;
;                     const int bl = r >> 13, t = r & 8191; const int pr = (bl << 13) + ((t & ((1 << dsh) - 1)) << (13 - dsh)) + (t >> dsh);
;                     bf16_t* rowp = O + (size_t)blk * SEC + (size_t)pr * 1024 + cin;
; #pragma unroll
;                     for (int bj = 0; bj < 2; ++bj) { const f32x4 v0 = v[bj][0] * gn[bj][0] * r2, v1 = v[bj][1] * gn[bj][1] * r2;
;                         u32x4 w; w.x = cvt_pk_bf16(v0[0], v0[1]); w.y = cvt_pk_bf16(v0[2], v0[3]); w.z = cvt_pk_bf16(v1[0], v1[1]); w.w = cvt_pk_bf16(v1[2], v1[3]);
;                         *(u32x4*)(rowp + bj * 32) = w; }
	v_pk_mul_f32 v[124:125], v[124:125], v[132:133] op_sel_hi:[1,0]
	v_pk_fma_f32 v[222:223], v[124:125], v[124:125], v[222:223]
	v_pk_mul_f32 v[126:127], v[122:123], v[132:133] op_sel_hi:[1,0]
	v_pk_fma_f32 v[222:223], v[126:127], v[126:127], v[222:223]
	v_pk_mul_f32 v[120:121], v[120:121], v[132:133] op_sel_hi:[1,0]
	v_pk_fma_f32 v[222:223], v[120:121], v[120:121], v[222:223]
	v_pk_mul_f32 v[122:123], v[118:119], v[132:133] op_sel_hi:[1,0]
	v_pk_fma_f32 v[222:223], v[122:123], v[122:123], v[222:223]
	v_pk_mul_f32 v[116:117], v[116:117], v[132:133] op_sel_hi:[1,0]
	v_pk_fma_f32 v[222:223], v[116:117], v[116:117], v[222:223]
	v_pk_mul_f32 v[118:119], v[114:115], v[132:133] op_sel_hi:[1,0]
	v_pk_fma_f32 v[222:223], v[118:119], v[118:119], v[222:223]
	v_add_f32_e32 v114, v222, v223
	v_mov_b32_e32 v115, v114
	s_nop 1
	v_permlane16_swap_b32_e32 v114, v115
	v_add_f32_e32 v114, v114, v115
	v_mov_b32_e32 v115, v114
	s_nop 1
	v_permlane32_swap_b32_e32 v114, v115
	v_add_f32_e32 v114, v114, v115
	v_fmamk_f32 v114, v114, 0x3c800000, v229
	v_rsq_f32_e32 v114, v114
	s_nop 0
	v_mul_f32_e32 v114, v171, v114
	v_cndmask_b32_e64 v114, 1.0, v114, s[40:41]
	v_pk_mul_f32 v[130:131], v[92:93], v[130:131]
	v_pk_mul_f32 v[128:129], v[94:95], v[128:129]
	v_pk_mul_f32 v[126:127], v[88:89], v[126:127]
	v_pk_mul_f32 v[124:125], v[90:91], v[124:125]
	v_pk_mul_f32 v[128:129], v[128:129], v[114:115] op_sel_hi:[1,0]
	v_pk_mul_f32 v[130:131], v[130:131], v[114:115] op_sel_hi:[1,0]
	v_pk_mul_f32 v[134:135], v[124:125], v[114:115] op_sel_hi:[1,0]
	v_pk_mul_f32 v[126:127], v[126:127], v[114:115] op_sel_hi:[1,0]
	v_cvt_pk_bf16_f32 v184, v130, v131
	v_cvt_pk_bf16_f32 v185, v128, v129
	v_pk_mul_f32 v[118:119], v[80:81], v[118:119]
	v_pk_mul_f32 v[116:117], v[82:83], v[116:117]
	v_cvt_pk_bf16_f32 v186, v126, v127
	v_cvt_pk_bf16_f32 v187, v134, v135
	v_pk_mul_f32 v[122:123], v[84:85], v[122:123]
	v_pk_mul_f32 v[120:121], v[86:87], v[120:121]
	v_pk_mul_f32 v[124:125], v[116:117], v[114:115] op_sel_hi:[1,0]
	v_pk_mul_f32 v[116:117], v[118:119], v[114:115] op_sel_hi:[1,0]
	v_pk_mul_f32 v[120:121], v[120:121], v[114:115] op_sel_hi:[1,0]
	v_pk_mul_f32 v[122:123], v[122:123], v[114:115] op_sel_hi:[1,0]
	s_movk_i32 s2, 0x1fef
	v_cvt_pk_bf16_f32 v114, v122, v123
	v_cvt_pk_bf16_f32 v115, v120, v121
	v_cvt_pk_bf16_f32 v116, v116, v117
	v_cvt_pk_bf16_f32 v117, v124, v125
	v_mov_b32_dpp v180, v184 row_ror:8 row_mask:0xf bank_mask:0xf
	v_mov_b32_dpp v181, v185 row_ror:8 row_mask:0xf bank_mask:0xf
	v_mov_b32_dpp v182, v186 row_ror:8 row_mask:0xf bank_mask:0xf
	v_mov_b32_dpp v183, v187 row_ror:8 row_mask:0xf bank_mask:0xf
	v_lshl_add_u64 v[212:213], v[174:175], 0, v[218:219]
	v_mov_b32_dpp v184, v114 row_ror:8 row_mask:0xf bank_mask:0xc
	v_mov_b32_dpp v185, v115 row_ror:8 row_mask:0xf bank_mask:0xc
	v_mov_b32_dpp v186, v116 row_ror:8 row_mask:0xf bank_mask:0xc
	v_mov_b32_dpp v187, v117 row_ror:8 row_mask:0xf bank_mask:0xc
	v_lshl_add_u64 v[214:215], v[174:175], 0, v[220:221]
	v_cndmask_b32_e32 v114, v180, v114, vcc
	v_cndmask_b32_e32 v115, v181, v115, vcc
	v_cndmask_b32_e32 v116, v182, v116, vcc
	v_cndmask_b32_e32 v117, v183, v117, vcc
	s_nop 0
	global_store_dwordx4 v[212:213], v[184:187], off nt
	global_store_dwordx4 v[214:215], v[114:117], off nt
	v_lshl_add_u64 v[174:175], v[174:175], 0, v[176:177]
	s_nop 1
	v_or_b32_e32 v117, 32, v160
	v_cvt_f32_u32_e32 v115, v197
	v_cvt_f32_u32_e32 v114, v196
	v_fmamk_f32 v114, v115, 0x4f800000, v114
	v_fmamk_f32 v114, v114, 0x30800000, v229
	v_rsq_f32_e32 v116, v114
	s_nop 0
	v_pk_mul_f32 v[110:111], v[110:111], v[116:117] op_sel_hi:[1,0]
	v_pk_mul_f32 v[222:223], v[110:111], v[110:111]
	v_pk_mul_f32 v[114:115], v[108:109], v[116:117] op_sel_hi:[1,0]
	v_pk_fma_f32 v[222:223], v[114:115], v[114:115], v[222:223]
	v_pk_mul_f32 v[106:107], v[106:107], v[116:117] op_sel_hi:[1,0]
	v_pk_fma_f32 v[222:223], v[106:107], v[106:107], v[222:223]
	v_pk_mul_f32 v[108:109], v[104:105], v[116:117] op_sel_hi:[1,0]
	v_pk_fma_f32 v[222:223], v[108:109], v[108:109], v[222:223]
	v_pk_mul_f32 v[102:103], v[102:103], v[116:117] op_sel_hi:[1,0]
	v_pk_fma_f32 v[222:223], v[102:103], v[102:103], v[222:223]
	v_pk_mul_f32 v[104:105], v[100:101], v[116:117] op_sel_hi:[1,0]
	v_pk_fma_f32 v[222:223], v[104:105], v[104:105], v[222:223]
	v_pk_mul_f32 v[98:99], v[98:99], v[116:117] op_sel_hi:[1,0]
	v_pk_fma_f32 v[222:223], v[98:99], v[98:99], v[222:223]
	v_pk_mul_f32 v[100:101], v[96:97], v[116:117] op_sel_hi:[1,0]
	v_pk_fma_f32 v[222:223], v[100:101], v[100:101], v[222:223]
	v_add_f32_e32 v96, v222, v223
	v_mov_b32_e32 v97, v96
	s_nop 1
	v_permlane16_swap_b32_e32 v96, v97
	v_add_f32_e32 v96, v96, v97
	v_mov_b32_e32 v97, v96
	s_nop 1
	v_permlane32_swap_b32_e32 v96, v97
	v_add_f32_e32 v96, v96, v97
	v_fmamk_f32 v96, v96, 0x3c800000, v229
	v_rsq_f32_e32 v96, v96
	s_nop 0
	v_mul_f32_e32 v96, v171, v96
	v_cndmask_b32_e64 v96, 1.0, v96, s[40:41]
	v_pk_mul_f32 v[114:115], v[92:93], v[114:115]
	v_pk_mul_f32 v[110:111], v[94:95], v[110:111]
	v_pk_mul_f32 v[108:109], v[88:89], v[108:109]
	v_pk_mul_f32 v[106:107], v[90:91], v[106:107]
	v_pk_mul_f32 v[110:111], v[110:111], v[96:97] op_sel_hi:[1,0]
	v_pk_mul_f32 v[114:115], v[114:115], v[96:97] op_sel_hi:[1,0]
	v_pk_mul_f32 v[118:119], v[106:107], v[96:97] op_sel_hi:[1,0]
	v_pk_mul_f32 v[108:109], v[108:109], v[96:97] op_sel_hi:[1,0]
	v_cvt_pk_bf16_f32 v184, v114, v115
	v_cvt_pk_bf16_f32 v185, v110, v111
	v_pk_mul_f32 v[100:101], v[80:81], v[100:101]
	v_pk_mul_f32 v[98:99], v[82:83], v[98:99]
	v_cvt_pk_bf16_f32 v186, v108, v109
	v_cvt_pk_bf16_f32 v187, v118, v119
	v_pk_mul_f32 v[104:105], v[84:85], v[104:105]
	v_pk_mul_f32 v[102:103], v[86:87], v[102:103]
; __device__ __forceinline__ unsigned cvt_pk_bf16(float lo, float hi) { unsigned r; asm volatile("v_cvt_pk_bf16_f32 %0, %1, %2" : "=v"(r) : "v"(lo), "v"(hi)); return r; }
; DI float x16_sum(float x) { const unsigned u = __builtin_bit_cast(unsigned, x); auto r = __builtin_amdgcn_permlane16_swap(u, u, false, false); return __builtin_bit_cast(float, (unsigned)r[0]) + __builtin_bit_cast(float, (unsigned)r[1]); }
; DI float x32_sum(float x) { const unsigned u = __builtin_bit_cast(unsigned, x); auto r = __builtin_amdgcn_permlane32_swap(u, u, false, false); return __builtin_bit_cast(float, (unsigned)r[0]) + __builtin_bit_cast(float, (unsigned)r[1]); }
;     __device__ __forceinline__ void operator()(const f32x4 (&acc)[2][2][4][2], const Unit& u, int wr, int wc, int fr, int fq) const {
;     ...
;                     const int r = row0 + ai * HALF + m * 16;
;                     const float rs = __builtin_amdgcn_rsqf((float)ss[r] * (1.0f / 1048576.0f) * (1.0f / 1024.0f) + EPS);
;                     f32x4 v[2][2]; float sq = 0.f;
; #pragma unroll
;                     for (int bj = 0; bj < 2; ++bj)
; #pragma unroll
;                         for (int n = 0; n < 2; ++n) { v[bj][n] = acc[ai][bj][m][n] * rs; sq += (v[bj][n][0] * v[bj][n][0] + v[bj][n][1] * v[bj][n][1]) + (v[bj][n][2] * v[bj][n][2] + v[bj][n][3] * v[bj][n][3]); }
;                     sq = x16_sum(sq); sq = x32_sum(sq);
;                     const float r2 = (sec < 2) ? qsc * __builtin_amdgcn_rsqf(sq * (1.0f / 64.0f) + EPS) : 1.0f;
;                     const int bl = r >> 13, t = r & 8191; const int pr = (bl << 13) + ((t & ((1 << dsh) - 1)) << (13 - dsh)) + (t >> dsh);
;                     bf16_t* rowp = O + (size_t)blk * SEC + (size_t)pr * 1024 + cin;
; #pragma unroll
;                     for (int bj = 0; bj < 2; ++bj) { const f32x4 v0 = v[bj][0] * gn[bj][0] * r2, v1 = v[bj][1] * gn[bj][1] * r2;
;                         u32x4 w; w.x = cvt_pk_bf16(v0[0], v0[1]); w.y = cvt_pk_bf16(v0[2], v0[3]); w.z = cvt_pk_bf16(v1[0], v1[1]); w.w = cvt_pk_bf16(v1[2], v1[3]);
;                         *(u32x4*)(rowp + bj * 32) = w; }
	v_pk_mul_f32 v[106:107], v[98:99], v[96:97] op_sel_hi:[1,0]
	v_pk_mul_f32 v[98:99], v[100:101], v[96:97] op_sel_hi:[1,0]
	v_pk_mul_f32 v[102:103], v[102:103], v[96:97] op_sel_hi:[1,0]
	v_pk_mul_f32 v[104:105], v[104:105], v[96:97] op_sel_hi:[1,0]
	s_movk_i32 s2, 0x1fff
	v_cvt_pk_bf16_f32 v96, v104, v105
	v_cvt_pk_bf16_f32 v97, v102, v103
	v_cvt_pk_bf16_f32 v98, v98, v99
	v_cvt_pk_bf16_f32 v99, v106, v107
	v_mov_b32_dpp v180, v184 row_ror:8 row_mask:0xf bank_mask:0xf
	v_mov_b32_dpp v181, v185 row_ror:8 row_mask:0xf bank_mask:0xf
	v_mov_b32_dpp v182, v186 row_ror:8 row_mask:0xf bank_mask:0xf
	v_mov_b32_dpp v183, v187 row_ror:8 row_mask:0xf bank_mask:0xf
	v_lshl_add_u64 v[212:213], v[174:175], 0, v[218:219]
	v_mov_b32_dpp v184, v96 row_ror:8 row_mask:0xf bank_mask:0xc
	v_mov_b32_dpp v185, v97 row_ror:8 row_mask:0xf bank_mask:0xc
	v_mov_b32_dpp v186, v98 row_ror:8 row_mask:0xf bank_mask:0xc
	v_mov_b32_dpp v187, v99 row_ror:8 row_mask:0xf bank_mask:0xc
	v_lshl_add_u64 v[214:215], v[174:175], 0, v[220:221]
	v_cndmask_b32_e32 v96, v180, v96, vcc
	v_cndmask_b32_e32 v97, v181, v97, vcc
	v_cndmask_b32_e32 v98, v182, v98, vcc
	v_cndmask_b32_e32 v99, v183, v99, vcc
	s_nop 0
	global_store_dwordx4 v[212:213], v[184:187], off nt
	global_store_dwordx4 v[214:215], v[96:99], off nt
	v_lshl_add_u64 v[174:175], v[174:175], 0, v[176:177]
	s_nop 1
	v_or_b32_e32 v99, 48, v160
	v_cvt_f32_u32_e32 v97, v199
	v_cvt_f32_u32_e32 v96, v198
	v_fmamk_f32 v96, v97, 0x4f800000, v96
	v_fmamk_f32 v96, v96, 0x30800000, v229
	v_rsq_f32_e32 v98, v96
	s_nop 0
	v_pk_mul_f32 v[78:79], v[78:79], v[98:99] op_sel_hi:[1,0]
	v_pk_mul_f32 v[222:223], v[78:79], v[78:79]
	v_pk_mul_f32 v[96:97], v[76:77], v[98:99] op_sel_hi:[1,0]
	v_pk_fma_f32 v[222:223], v[96:97], v[96:97], v[222:223]
	v_pk_mul_f32 v[74:75], v[74:75], v[98:99] op_sel_hi:[1,0]
	v_pk_fma_f32 v[222:223], v[74:75], v[74:75], v[222:223]
	v_pk_mul_f32 v[76:77], v[72:73], v[98:99] op_sel_hi:[1,0]
	v_pk_fma_f32 v[222:223], v[76:77], v[76:77], v[222:223]
	v_pk_mul_f32 v[70:71], v[70:71], v[98:99] op_sel_hi:[1,0]
	v_pk_fma_f32 v[222:223], v[70:71], v[70:71], v[222:223]
	v_pk_mul_f32 v[72:73], v[68:69], v[98:99] op_sel_hi:[1,0]
	v_pk_fma_f32 v[222:223], v[72:73], v[72:73], v[222:223]
	v_pk_mul_f32 v[66:67], v[66:67], v[98:99] op_sel_hi:[1,0]
	v_pk_fma_f32 v[222:223], v[66:67], v[66:67], v[222:223]
	v_pk_mul_f32 v[68:69], v[64:65], v[98:99] op_sel_hi:[1,0]
	v_pk_fma_f32 v[222:223], v[68:69], v[68:69], v[222:223]
	v_add_f32_e32 v64, v222, v223
	v_mov_b32_e32 v65, v64
	s_nop 1
	v_permlane16_swap_b32_e32 v64, v65
	v_add_f32_e32 v64, v64, v65
	v_mov_b32_e32 v65, v64
	s_nop 1
	v_permlane32_swap_b32_e32 v64, v65
	v_add_f32_e32 v64, v64, v65
	v_fmamk_f32 v64, v64, 0x3c800000, v229
	v_rsq_f32_e32 v64, v64
	s_nop 0
	v_mul_f32_e32 v64, v171, v64
	v_cndmask_b32_e64 v64, 1.0, v64, s[40:41]
	v_pk_mul_f32 v[96:97], v[92:93], v[96:97]
	v_pk_mul_f32 v[78:79], v[94:95], v[78:79]
	v_pk_mul_f32 v[76:77], v[88:89], v[76:77]
	v_pk_mul_f32 v[74:75], v[90:91], v[74:75]
	v_pk_mul_f32 v[78:79], v[78:79], v[64:65] op_sel_hi:[1,0]
	v_pk_mul_f32 v[96:97], v[96:97], v[64:65] op_sel_hi:[1,0]
	v_pk_mul_f32 v[100:101], v[74:75], v[64:65] op_sel_hi:[1,0]
	v_pk_mul_f32 v[76:77], v[76:77], v[64:65] op_sel_hi:[1,0]
	v_cvt_pk_bf16_f32 v184, v96, v97
	v_cvt_pk_bf16_f32 v185, v78, v79
	v_pk_mul_f32 v[68:69], v[80:81], v[68:69]
	v_pk_mul_f32 v[66:67], v[82:83], v[66:67]
	v_cvt_pk_bf16_f32 v186, v76, v77
	v_cvt_pk_bf16_f32 v187, v100, v101
	v_pk_mul_f32 v[72:73], v[84:85], v[72:73]
	v_pk_mul_f32 v[70:71], v[86:87], v[70:71]
	v_pk_mul_f32 v[74:75], v[66:67], v[64:65] op_sel_hi:[1,0]
	v_pk_mul_f32 v[66:67], v[68:69], v[64:65] op_sel_hi:[1,0]
	v_pk_mul_f32 v[70:71], v[70:71], v[64:65] op_sel_hi:[1,0]
	v_pk_mul_f32 v[72:73], v[72:73], v[64:65] op_sel_hi:[1,0]
	s_nop 0
	v_cvt_pk_bf16_f32 v64, v72, v73
	v_cvt_pk_bf16_f32 v65, v70, v71
	v_cvt_pk_bf16_f32 v66, v66, v67
	v_cvt_pk_bf16_f32 v67, v74, v75
	v_mov_b32_dpp v180, v184 row_ror:8 row_mask:0xf bank_mask:0xf
	v_mov_b32_dpp v181, v185 row_ror:8 row_mask:0xf bank_mask:0xf
	v_mov_b32_dpp v182, v186 row_ror:8 row_mask:0xf bank_mask:0xf
	v_mov_b32_dpp v183, v187 row_ror:8 row_mask:0xf bank_mask:0xf
	v_lshl_add_u64 v[212:213], v[174:175], 0, v[218:219]
	v_mov_b32_dpp v184, v64 row_ror:8 row_mask:0xf bank_mask:0xc
	v_mov_b32_dpp v185, v65 row_ror:8 row_mask:0xf bank_mask:0xc
	v_mov_b32_dpp v186, v66 row_ror:8 row_mask:0xf bank_mask:0xc
	v_mov_b32_dpp v187, v67 row_ror:8 row_mask:0xf bank_mask:0xc
	v_lshl_add_u64 v[214:215], v[174:175], 0, v[220:221]
	v_cndmask_b32_e32 v64, v180, v64, vcc
	v_cndmask_b32_e32 v65, v181, v65, vcc
	v_cndmask_b32_e32 v66, v182, v66, vcc
	v_cndmask_b32_e32 v67, v183, v67, vcc
	s_nop 0
	global_store_dwordx4 v[212:213], v[184:187], off nt
	global_store_dwordx4 v[214:215], v[64:67], off nt
	v_lshl_add_u64 v[174:175], v[174:175], 0, v[178:179]
	s_nop 1
	v_add_u32_e32 v67, 0x80, v160
	v_cvt_f32_u32_e32 v65, v201
	v_cvt_f32_u32_e32 v64, v200
	v_fmamk_f32 v64, v65, 0x4f800000, v64
	v_fmamk_f32 v64, v64, 0x30800000, v229
	v_rsq_f32_e32 v66, v64
	s_nop 0
	v_pk_mul_f32 v[62:63], v[62:63], v[66:67] op_sel_hi:[1,0]
	v_pk_mul_f32 v[222:223], v[62:63], v[62:63]
	v_pk_mul_f32 v[64:65], v[60:61], v[66:67] op_sel_hi:[1,0]
	v_pk_fma_f32 v[222:223], v[64:65], v[64:65], v[222:223]
	v_pk_mul_f32 v[58:59], v[58:59], v[66:67] op_sel_hi:[1,0]
	v_pk_fma_f32 v[222:223], v[58:59], v[58:59], v[222:223]
	v_pk_mul_f32 v[60:61], v[56:57], v[66:67] op_sel_hi:[1,0]
	v_pk_fma_f32 v[222:223], v[60:61], v[60:61], v[222:223]
	v_pk_mul_f32 v[54:55], v[54:55], v[66:67] op_sel_hi:[1,0]
	v_pk_fma_f32 v[222:223], v[54:55], v[54:55], v[222:223]
; __device__ __forceinline__ unsigned cvt_pk_bf16(float lo, float hi) { unsigned r; asm volatile("v_cvt_pk_bf16_f32 %0, %1, %2" : "=v"(r) : "v"(lo), "v"(hi)); return r; }
; DI float x16_sum(float x) { const unsigned u = __builtin_bit_cast(unsigned, x); auto r = __builtin_amdgcn_permlane16_swap(u, u, false, false); return __builtin_bit_cast(float, (unsigned)r[0]) + __builtin_bit_cast(float, (unsigned)r[1]); }
; DI float x32_sum(float x) { const unsigned u = __builtin_bit_cast(unsigned, x); auto r = __builtin_amdgcn_permlane32_swap(u, u, false, false); return __builtin_bit_cast(float, (unsigned)r[0]) + __builtin_bit_cast(float, (unsigned)r[1]); }
;     __device__ __forceinline__ void operator()(const f32x4 (&acc)[2][2][4][2], const Unit& u, int wr, int wc, int fr, int fq) const {
;     ...
;                     const int r = row0 + ai * HALF + m * 16;
;                     const float rs = __builtin_amdgcn_rsqf((float)ss[r] * (1.0f / 1048576.0f) * (1.0f / 1024.0f) + EPS);
;                     f32x4 v[2][2]; float sq = 0.f;
; #pragma unroll
;                     for (int bj = 0; bj < 2; ++bj)
; #pragma unroll
;                         for (int n = 0; n < 2; ++n) { v[bj][n] = acc[ai][bj][m][n] * rs; sq += (v[bj][n][0] * v[bj][n][0] + v[bj][n][1] * v[bj][n][1]) + (v[bj][n][2] * v[bj][n][2] + v[bj][n][3] * v[bj][n][3]); }
;                     sq = x16_sum(sq); sq = x32_sum(sq);
;                     const float r2 = (sec < 2) ? qsc * __builtin_amdgcn_rsqf(sq * (1.0f / 64.0f) + EPS) : 1.0f;
;                     const int bl = r >> 13, t = r & 8191; const int pr = (bl << 13) + ((t & ((1 << dsh) - 1)) << (13 - dsh)) + (t >> dsh);
;                     bf16_t* rowp = O + (size_t)blk * SEC + (size_t)pr * 1024 + cin;
; #pragma unroll
;                     for (int bj = 0; bj < 2; ++bj) { const f32x4 v0 = v[bj][0] * gn[bj][0] * r2, v1 = v[bj][1] * gn[bj][1] * r2;
;                         u32x4 w; w.x = cvt_pk_bf16(v0[0], v0[1]); w.y = cvt_pk_bf16(v0[2], v0[3]); w.z = cvt_pk_bf16(v1[0], v1[1]); w.w = cvt_pk_bf16(v1[2], v1[3]);
;                         *(u32x4*)(rowp + bj * 32) = w; }
	v_pk_mul_f32 v[56:57], v[52:53], v[66:67] op_sel_hi:[1,0]
	v_pk_fma_f32 v[222:223], v[56:57], v[56:57], v[222:223]
	v_pk_mul_f32 v[50:51], v[50:51], v[66:67] op_sel_hi:[1,0]
	v_pk_fma_f32 v[222:223], v[50:51], v[50:51], v[222:223]
	v_pk_mul_f32 v[52:53], v[48:49], v[66:67] op_sel_hi:[1,0]
	v_pk_fma_f32 v[222:223], v[52:53], v[52:53], v[222:223]
	v_add_f32_e32 v48, v222, v223
	v_mov_b32_e32 v49, v48
	s_nop 1
	v_permlane16_swap_b32_e32 v48, v49
	v_add_f32_e32 v48, v48, v49
	v_mov_b32_e32 v49, v48
	s_nop 1
	v_permlane32_swap_b32_e32 v48, v49
	v_add_f32_e32 v48, v48, v49
	v_fmamk_f32 v48, v48, 0x3c800000, v229
	v_rsq_f32_e32 v48, v48
	s_nop 0
	v_mul_f32_e32 v48, v171, v48
	v_cndmask_b32_e64 v48, 1.0, v48, s[40:41]
	v_pk_mul_f32 v[64:65], v[92:93], v[64:65]
	v_pk_mul_f32 v[62:63], v[94:95], v[62:63]
	v_pk_mul_f32 v[60:61], v[88:89], v[60:61]
	v_pk_mul_f32 v[58:59], v[90:91], v[58:59]
	v_pk_mul_f32 v[62:63], v[62:63], v[48:49] op_sel_hi:[1,0]
	v_pk_mul_f32 v[64:65], v[64:65], v[48:49] op_sel_hi:[1,0]
	v_pk_mul_f32 v[70:71], v[58:59], v[48:49] op_sel_hi:[1,0]
	v_pk_mul_f32 v[60:61], v[60:61], v[48:49] op_sel_hi:[1,0]
	v_cvt_pk_bf16_f32 v184, v64, v65
	v_cvt_pk_bf16_f32 v185, v62, v63
	v_pk_mul_f32 v[52:53], v[80:81], v[52:53]
	v_pk_mul_f32 v[50:51], v[82:83], v[50:51]
	v_cvt_pk_bf16_f32 v186, v60, v61
	v_cvt_pk_bf16_f32 v187, v70, v71
	v_pk_mul_f32 v[56:57], v[84:85], v[56:57]
	v_pk_mul_f32 v[54:55], v[86:87], v[54:55]
	v_pk_mul_f32 v[58:59], v[50:51], v[48:49] op_sel_hi:[1,0]
	v_pk_mul_f32 v[50:51], v[52:53], v[48:49] op_sel_hi:[1,0]
	v_pk_mul_f32 v[54:55], v[54:55], v[48:49] op_sel_hi:[1,0]
	v_pk_mul_f32 v[56:57], v[56:57], v[48:49] op_sel_hi:[1,0]
	s_nop 0
	v_cvt_pk_bf16_f32 v48, v56, v57
	v_cvt_pk_bf16_f32 v49, v54, v55
	v_cvt_pk_bf16_f32 v50, v50, v51
	v_cvt_pk_bf16_f32 v51, v58, v59
	v_mov_b32_dpp v180, v184 row_ror:8 row_mask:0xf bank_mask:0xf
	v_mov_b32_dpp v181, v185 row_ror:8 row_mask:0xf bank_mask:0xf
	v_mov_b32_dpp v182, v186 row_ror:8 row_mask:0xf bank_mask:0xf
	v_mov_b32_dpp v183, v187 row_ror:8 row_mask:0xf bank_mask:0xf
	v_lshl_add_u64 v[212:213], v[174:175], 0, v[218:219]
	v_mov_b32_dpp v184, v48 row_ror:8 row_mask:0xf bank_mask:0xc
	v_mov_b32_dpp v185, v49 row_ror:8 row_mask:0xf bank_mask:0xc
	v_mov_b32_dpp v186, v50 row_ror:8 row_mask:0xf bank_mask:0xc
	v_mov_b32_dpp v187, v51 row_ror:8 row_mask:0xf bank_mask:0xc
	v_lshl_add_u64 v[214:215], v[174:175], 0, v[220:221]
	v_cndmask_b32_e32 v48, v180, v48, vcc
	v_cndmask_b32_e32 v49, v181, v49, vcc
	v_cndmask_b32_e32 v50, v182, v50, vcc
	v_cndmask_b32_e32 v51, v183, v51, vcc
	s_nop 0
	global_store_dwordx4 v[212:213], v[184:187], off nt
	global_store_dwordx4 v[214:215], v[48:51], off nt
	v_lshl_add_u64 v[174:175], v[174:175], 0, v[176:177]
	s_nop 1
	v_add_u32_e32 v51, 0x90, v160
	v_cvt_f32_u32_e32 v49, v203
	v_cvt_f32_u32_e32 v48, v202
	v_fmamk_f32 v48, v49, 0x4f800000, v48
	v_fmamk_f32 v48, v48, 0x30800000, v229
	v_rsq_f32_e32 v50, v48
	s_nop 0
	v_pk_mul_f32 v[46:47], v[46:47], v[50:51] op_sel_hi:[1,0]
	v_pk_mul_f32 v[222:223], v[46:47], v[46:47]
	v_pk_mul_f32 v[48:49], v[44:45], v[50:51] op_sel_hi:[1,0]
	v_pk_fma_f32 v[222:223], v[48:49], v[48:49], v[222:223]
	v_pk_mul_f32 v[42:43], v[42:43], v[50:51] op_sel_hi:[1,0]
	v_pk_fma_f32 v[222:223], v[42:43], v[42:43], v[222:223]
	v_pk_mul_f32 v[44:45], v[40:41], v[50:51] op_sel_hi:[1,0]
	v_pk_fma_f32 v[222:223], v[44:45], v[44:45], v[222:223]
	v_pk_mul_f32 v[38:39], v[38:39], v[50:51] op_sel_hi:[1,0]
	v_pk_fma_f32 v[222:223], v[38:39], v[38:39], v[222:223]
	v_pk_mul_f32 v[40:41], v[36:37], v[50:51] op_sel_hi:[1,0]
	v_pk_fma_f32 v[222:223], v[40:41], v[40:41], v[222:223]
	v_pk_mul_f32 v[34:35], v[34:35], v[50:51] op_sel_hi:[1,0]
	v_pk_fma_f32 v[222:223], v[34:35], v[34:35], v[222:223]
	v_pk_mul_f32 v[36:37], v[32:33], v[50:51] op_sel_hi:[1,0]
	v_pk_fma_f32 v[222:223], v[36:37], v[36:37], v[222:223]
	v_add_f32_e32 v32, v222, v223
	v_mov_b32_e32 v33, v32
	s_nop 1
	v_permlane16_swap_b32_e32 v32, v33
	v_add_f32_e32 v32, v32, v33
	v_mov_b32_e32 v33, v32
	s_nop 1
	v_permlane32_swap_b32_e32 v32, v33
	v_add_f32_e32 v32, v32, v33
	v_fmamk_f32 v32, v32, 0x3c800000, v229
	v_rsq_f32_e32 v32, v32
	s_nop 0
	v_mul_f32_e32 v32, v171, v32
	v_cndmask_b32_e64 v32, 1.0, v32, s[40:41]
	v_pk_mul_f32 v[48:49], v[92:93], v[48:49]
	v_pk_mul_f32 v[46:47], v[94:95], v[46:47]
	v_pk_mul_f32 v[44:45], v[88:89], v[44:45]
	v_pk_mul_f32 v[42:43], v[90:91], v[42:43]
	v_pk_mul_f32 v[46:47], v[46:47], v[32:33] op_sel_hi:[1,0]
	v_pk_mul_f32 v[48:49], v[48:49], v[32:33] op_sel_hi:[1,0]
	v_pk_mul_f32 v[52:53], v[42:43], v[32:33] op_sel_hi:[1,0]
	v_pk_mul_f32 v[44:45], v[44:45], v[32:33] op_sel_hi:[1,0]
	v_cvt_pk_bf16_f32 v184, v48, v49
	v_cvt_pk_bf16_f32 v185, v46, v47
	v_pk_mul_f32 v[36:37], v[80:81], v[36:37]
	v_pk_mul_f32 v[34:35], v[82:83], v[34:35]
	v_cvt_pk_bf16_f32 v186, v44, v45
	v_cvt_pk_bf16_f32 v187, v52, v53
	v_pk_mul_f32 v[40:41], v[84:85], v[40:41]
	v_pk_mul_f32 v[38:39], v[86:87], v[38:39]
	v_pk_mul_f32 v[42:43], v[34:35], v[32:33] op_sel_hi:[1,0]
	v_pk_mul_f32 v[34:35], v[36:37], v[32:33] op_sel_hi:[1,0]
	v_pk_mul_f32 v[38:39], v[38:39], v[32:33] op_sel_hi:[1,0]
	v_pk_mul_f32 v[40:41], v[40:41], v[32:33] op_sel_hi:[1,0]
	s_nop 0
	v_cvt_pk_bf16_f32 v32, v40, v41
	v_cvt_pk_bf16_f32 v33, v38, v39
	v_cvt_pk_bf16_f32 v34, v34, v35
	v_cvt_pk_bf16_f32 v35, v42, v43
	v_mov_b32_dpp v180, v184 row_ror:8 row_mask:0xf bank_mask:0xf
	v_mov_b32_dpp v181, v185 row_ror:8 row_mask:0xf bank_mask:0xf
	v_mov_b32_dpp v182, v186 row_ror:8 row_mask:0xf bank_mask:0xf
	v_mov_b32_dpp v183, v187 row_ror:8 row_mask:0xf bank_mask:0xf
	v_lshl_add_u64 v[212:213], v[174:175], 0, v[218:219]
; __device__ __forceinline__ unsigned cvt_pk_bf16(float lo, float hi) { unsigned r; asm volatile("v_cvt_pk_bf16_f32 %0, %1, %2" : "=v"(r) : "v"(lo), "v"(hi)); return r; }
; DI float x16_sum(float x) { const unsigned u = __builtin_bit_cast(unsigned, x); auto r = __builtin_amdgcn_permlane16_swap(u, u, false, false); return __builtin_bit_cast(float, (unsigned)r[0]) + __builtin_bit_cast(float, (unsigned)r[1]); }
; DI float x32_sum(float x) { const unsigned u = __builtin_bit_cast(unsigned, x); auto r = __builtin_amdgcn_permlane32_swap(u, u, false, false); return __builtin_bit_cast(float, (unsigned)r[0]) + __builtin_bit_cast(float, (unsigned)r[1]); }
;     __device__ __forceinline__ void operator()(const f32x4 (&acc)[2][2][4][2], const Unit& u, int wr, int wc, int fr, int fq) const {
;     ...
;                     const int r = row0 + ai * HALF + m * 16;
;                     const float rs = __builtin_amdgcn_rsqf((float)ss[r] * (1.0f / 1048576.0f) * (1.0f / 1024.0f) + EPS);
;                     f32x4 v[2][2]; float sq = 0.f;
; #pragma unroll
;                     for (int bj = 0; bj < 2; ++bj)
; #pragma unroll
;                         for (int n = 0; n < 2; ++n) { v[bj][n] = acc[ai][bj][m][n] * rs; sq += (v[bj][n][0] * v[bj][n][0] + v[bj][n][1] * v[bj][n][1]) + (v[bj][n][2] * v[bj][n][2] + v[bj][n][3] * v[bj][n][3]); }
;                     sq = x16_sum(sq); sq = x32_sum(sq);
;                     const float r2 = (sec < 2) ? qsc * __builtin_amdgcn_rsqf(sq * (1.0f / 64.0f) + EPS) : 1.0f;
;                     const int bl = r >> 13, t = r & 8191; const int pr = (bl << 13) + ((t & ((1 << dsh) - 1)) << (13 - dsh)) + (t >> dsh);
;                     bf16_t* rowp = O + (size_t)blk * SEC + (size_t)pr * 1024 + cin;
; #pragma unroll
;                     for (int bj = 0; bj < 2; ++bj) { const f32x4 v0 = v[bj][0] * gn[bj][0] * r2, v1 = v[bj][1] * gn[bj][1] * r2;
;                         u32x4 w; w.x = cvt_pk_bf16(v0[0], v0[1]); w.y = cvt_pk_bf16(v0[2], v0[3]); w.z = cvt_pk_bf16(v1[0], v1[1]); w.w = cvt_pk_bf16(v1[2], v1[3]);
;                         *(u32x4*)(rowp + bj * 32) = w; }
	v_mov_b32_dpp v184, v32 row_ror:8 row_mask:0xf bank_mask:0xc
	v_mov_b32_dpp v185, v33 row_ror:8 row_mask:0xf bank_mask:0xc
	v_mov_b32_dpp v186, v34 row_ror:8 row_mask:0xf bank_mask:0xc
	v_mov_b32_dpp v187, v35 row_ror:8 row_mask:0xf bank_mask:0xc
	v_lshl_add_u64 v[214:215], v[174:175], 0, v[220:221]
	v_cndmask_b32_e32 v32, v180, v32, vcc
	v_cndmask_b32_e32 v33, v181, v33, vcc
	v_cndmask_b32_e32 v34, v182, v34, vcc
	v_cndmask_b32_e32 v35, v183, v35, vcc
	s_nop 0
	global_store_dwordx4 v[212:213], v[184:187], off nt
	global_store_dwordx4 v[214:215], v[32:35], off nt
	v_lshl_add_u64 v[174:175], v[174:175], 0, v[176:177]
	s_nop 1
	v_add_u32_e32 v35, 0xa0, v160
	v_cvt_f32_u32_e32 v33, v205
	v_cvt_f32_u32_e32 v32, v204
	v_fmamk_f32 v32, v33, 0x4f800000, v32
	v_fmamk_f32 v32, v32, 0x30800000, v229
	v_rsq_f32_e32 v34, v32
	s_nop 0
	v_pk_mul_f32 v[30:31], v[30:31], v[34:35] op_sel_hi:[1,0]
	v_pk_mul_f32 v[222:223], v[30:31], v[30:31]
	v_pk_mul_f32 v[32:33], v[28:29], v[34:35] op_sel_hi:[1,0]
	v_pk_fma_f32 v[222:223], v[32:33], v[32:33], v[222:223]
	v_pk_mul_f32 v[26:27], v[26:27], v[34:35] op_sel_hi:[1,0]
	v_pk_fma_f32 v[222:223], v[26:27], v[26:27], v[222:223]
	v_pk_mul_f32 v[28:29], v[24:25], v[34:35] op_sel_hi:[1,0]
	v_pk_fma_f32 v[222:223], v[28:29], v[28:29], v[222:223]
	v_pk_mul_f32 v[22:23], v[22:23], v[34:35] op_sel_hi:[1,0]
	v_pk_fma_f32 v[222:223], v[22:23], v[22:23], v[222:223]
	v_pk_mul_f32 v[24:25], v[20:21], v[34:35] op_sel_hi:[1,0]
	v_pk_fma_f32 v[222:223], v[24:25], v[24:25], v[222:223]
	v_pk_mul_f32 v[18:19], v[18:19], v[34:35] op_sel_hi:[1,0]
	v_pk_fma_f32 v[222:223], v[18:19], v[18:19], v[222:223]
	v_pk_mul_f32 v[20:21], v[16:17], v[34:35] op_sel_hi:[1,0]
	v_pk_fma_f32 v[222:223], v[20:21], v[20:21], v[222:223]
	v_add_f32_e32 v16, v222, v223
	v_mov_b32_e32 v17, v16
	s_nop 1
	v_permlane16_swap_b32_e32 v16, v17
	v_add_f32_e32 v16, v16, v17
	v_mov_b32_e32 v17, v16
	s_nop 1
	v_permlane32_swap_b32_e32 v16, v17
	v_add_f32_e32 v16, v16, v17
	v_fmamk_f32 v16, v16, 0x3c800000, v229
	v_rsq_f32_e32 v16, v16
	s_nop 0
	v_mul_f32_e32 v16, v171, v16
	v_cndmask_b32_e64 v16, 1.0, v16, s[40:41]
	v_pk_mul_f32 v[32:33], v[92:93], v[32:33]
	v_pk_mul_f32 v[30:31], v[94:95], v[30:31]
	v_pk_mul_f32 v[28:29], v[88:89], v[28:29]
	v_pk_mul_f32 v[26:27], v[90:91], v[26:27]
	v_pk_mul_f32 v[30:31], v[30:31], v[16:17] op_sel_hi:[1,0]
	v_pk_mul_f32 v[32:33], v[32:33], v[16:17] op_sel_hi:[1,0]
	v_pk_mul_f32 v[36:37], v[26:27], v[16:17] op_sel_hi:[1,0]
	v_pk_mul_f32 v[28:29], v[28:29], v[16:17] op_sel_hi:[1,0]
	v_cvt_pk_bf16_f32 v184, v32, v33
	v_cvt_pk_bf16_f32 v185, v30, v31
	v_pk_mul_f32 v[20:21], v[80:81], v[20:21]
	v_pk_mul_f32 v[18:19], v[82:83], v[18:19]
	v_cvt_pk_bf16_f32 v186, v28, v29
	v_cvt_pk_bf16_f32 v187, v36, v37
	v_pk_mul_f32 v[24:25], v[84:85], v[24:25]
	v_pk_mul_f32 v[22:23], v[86:87], v[22:23]
	v_pk_mul_f32 v[26:27], v[18:19], v[16:17] op_sel_hi:[1,0]
	v_pk_mul_f32 v[18:19], v[20:21], v[16:17] op_sel_hi:[1,0]
	v_pk_mul_f32 v[22:23], v[22:23], v[16:17] op_sel_hi:[1,0]
	v_pk_mul_f32 v[24:25], v[24:25], v[16:17] op_sel_hi:[1,0]
	s_nop 0
	v_cvt_pk_bf16_f32 v16, v24, v25
	v_cvt_pk_bf16_f32 v17, v22, v23
	v_cvt_pk_bf16_f32 v18, v18, v19
	v_cvt_pk_bf16_f32 v19, v26, v27
	v_mov_b32_dpp v180, v184 row_ror:8 row_mask:0xf bank_mask:0xf
	v_mov_b32_dpp v181, v185 row_ror:8 row_mask:0xf bank_mask:0xf
	v_mov_b32_dpp v182, v186 row_ror:8 row_mask:0xf bank_mask:0xf
	v_mov_b32_dpp v183, v187 row_ror:8 row_mask:0xf bank_mask:0xf
	v_lshl_add_u64 v[212:213], v[174:175], 0, v[218:219]
	v_mov_b32_dpp v184, v16 row_ror:8 row_mask:0xf bank_mask:0xc
	v_mov_b32_dpp v185, v17 row_ror:8 row_mask:0xf bank_mask:0xc
	v_mov_b32_dpp v186, v18 row_ror:8 row_mask:0xf bank_mask:0xc
	v_mov_b32_dpp v187, v19 row_ror:8 row_mask:0xf bank_mask:0xc
; __device__ __forceinline__ unsigned cvt_pk_bf16(float lo, float hi) { unsigned r; asm volatile("v_cvt_pk_bf16_f32 %0, %1, %2" : "=v"(r) : "v"(lo), "v"(hi)); return r; }
; DI float x16_sum(float x) { const unsigned u = __builtin_bit_cast(unsigned, x); auto r = __builtin_amdgcn_permlane16_swap(u, u, false, false); return __builtin_bit_cast(float, (unsigned)r[0]) + __builtin_bit_cast(float, (unsigned)r[1]); }
; DI float x32_sum(float x) { const unsigned u = __builtin_bit_cast(unsigned, x); auto r = __builtin_amdgcn_permlane32_swap(u, u, false, false); return __builtin_bit_cast(float, (unsigned)r[0]) + __builtin_bit_cast(float, (unsigned)r[1]); }
;     __device__ __forceinline__ void operator()(const f32x4 (&acc)[2][2][4][2], const Unit& u, int wr, int wc, int fr, int fq) const {
;     ...
;                     const int r = row0 + ai * HALF + m * 16;
;                     const float rs = __builtin_amdgcn_rsqf((float)ss[r] * (1.0f / 1048576.0f) * (1.0f / 1024.0f) + EPS);
;                     f32x4 v[2][2]; float sq = 0.f;
; #pragma unroll
;                     for (int bj = 0; bj < 2; ++bj)
; #pragma unroll
;                         for (int n = 0; n < 2; ++n) { v[bj][n] = acc[ai][bj][m][n] * rs; sq += (v[bj][n][0] * v[bj][n][0] + v[bj][n][1] * v[bj][n][1]) + (v[bj][n][2] * v[bj][n][2] + v[bj][n][3] * v[bj][n][3]); }
;                     sq = x16_sum(sq); sq = x32_sum(sq);
;                     const float r2 = (sec < 2) ? qsc * __builtin_amdgcn_rsqf(sq * (1.0f / 64.0f) + EPS) : 1.0f;
;                     const int bl = r >> 13, t = r & 8191; const int pr = (bl << 13) + ((t & ((1 << dsh) - 1)) << (13 - dsh)) + (t >> dsh);
;                     bf16_t* rowp = O + (size_t)blk * SEC + (size_t)pr * 1024 + cin;
; #pragma unroll
;                     for (int bj = 0; bj < 2; ++bj) { const f32x4 v0 = v[bj][0] * gn[bj][0] * r2, v1 = v[bj][1] * gn[bj][1] * r2;
;                         u32x4 w; w.x = cvt_pk_bf16(v0[0], v0[1]); w.y = cvt_pk_bf16(v0[2], v0[3]); w.z = cvt_pk_bf16(v1[0], v1[1]); w.w = cvt_pk_bf16(v1[2], v1[3]);
;                         *(u32x4*)(rowp + bj * 32) = w; }
	v_lshl_add_u64 v[214:215], v[174:175], 0, v[220:221]
	v_cndmask_b32_e32 v16, v180, v16, vcc
	v_cndmask_b32_e32 v17, v181, v17, vcc
	v_cndmask_b32_e32 v18, v182, v18, vcc
	v_cndmask_b32_e32 v19, v183, v19, vcc
	s_nop 0
	global_store_dwordx4 v[212:213], v[184:187], off nt
	global_store_dwordx4 v[214:215], v[16:19], off nt
	v_lshl_add_u64 v[174:175], v[174:175], 0, v[176:177]
	s_nop 1
	v_add_u32_e32 v19, 0xb0, v160
	v_cvt_f32_u32_e32 v17, v207
	v_cvt_f32_u32_e32 v16, v206
	v_fmamk_f32 v16, v17, 0x4f800000, v16
	v_fmamk_f32 v16, v16, 0x30800000, v229
	v_rsq_f32_e32 v18, v16
	s_nop 0
	v_pk_mul_f32 v[14:15], v[14:15], v[18:19] op_sel_hi:[1,0]
	v_pk_mul_f32 v[222:223], v[14:15], v[14:15]
	v_pk_mul_f32 v[16:17], v[12:13], v[18:19] op_sel_hi:[1,0]
	v_pk_fma_f32 v[222:223], v[16:17], v[16:17], v[222:223]
	v_pk_mul_f32 v[10:11], v[10:11], v[18:19] op_sel_hi:[1,0]
	v_pk_fma_f32 v[222:223], v[10:11], v[10:11], v[222:223]
	v_pk_mul_f32 v[12:13], v[8:9], v[18:19] op_sel_hi:[1,0]
	v_pk_fma_f32 v[222:223], v[12:13], v[12:13], v[222:223]
	v_pk_mul_f32 v[6:7], v[6:7], v[18:19] op_sel_hi:[1,0]
	v_pk_fma_f32 v[222:223], v[6:7], v[6:7], v[222:223]
	v_pk_mul_f32 v[8:9], v[4:5], v[18:19] op_sel_hi:[1,0]
	v_pk_fma_f32 v[222:223], v[8:9], v[8:9], v[222:223]
	v_pk_mul_f32 v[2:3], v[2:3], v[18:19] op_sel_hi:[1,0]
	v_pk_fma_f32 v[222:223], v[2:3], v[2:3], v[222:223]
	v_pk_mul_f32 v[4:5], v[0:1], v[18:19] op_sel_hi:[1,0]
	v_pk_fma_f32 v[222:223], v[4:5], v[4:5], v[222:223]
	v_add_f32_e32 v0, v222, v223
	v_mov_b32_e32 v1, v0
	s_nop 1
	v_permlane16_swap_b32_e32 v0, v1
	v_add_f32_e32 v0, v0, v1
	v_mov_b32_e32 v1, v0
	s_nop 1
	v_permlane32_swap_b32_e32 v0, v1
	v_add_f32_e32 v0, v0, v1
	v_fmamk_f32 v0, v0, 0x3c800000, v229
	v_rsq_f32_e32 v0, v0
	s_nop 0
	v_mul_f32_e32 v0, v171, v0
	v_cndmask_b32_e64 v0, 1.0, v0, s[40:41]
	v_pk_mul_f32 v[16:17], v[92:93], v[16:17]
	v_pk_mul_f32 v[14:15], v[94:95], v[14:15]
	v_pk_mul_f32 v[12:13], v[88:89], v[12:13]
	v_pk_mul_f32 v[10:11], v[90:91], v[10:11]
	v_pk_mul_f32 v[14:15], v[14:15], v[0:1] op_sel_hi:[1,0]
	v_pk_mul_f32 v[16:17], v[16:17], v[0:1] op_sel_hi:[1,0]
	v_pk_mul_f32 v[20:21], v[10:11], v[0:1] op_sel_hi:[1,0]
	v_pk_mul_f32 v[12:13], v[12:13], v[0:1] op_sel_hi:[1,0]
	v_cvt_pk_bf16_f32 v184, v16, v17
	v_cvt_pk_bf16_f32 v185, v14, v15
	v_pk_mul_f32 v[4:5], v[80:81], v[4:5]
	v_pk_mul_f32 v[2:3], v[82:83], v[2:3]
	v_cvt_pk_bf16_f32 v186, v12, v13
	v_cvt_pk_bf16_f32 v187, v20, v21
	v_pk_mul_f32 v[8:9], v[84:85], v[8:9]
	v_pk_mul_f32 v[6:7], v[86:87], v[6:7]
	v_pk_mul_f32 v[10:11], v[2:3], v[0:1] op_sel_hi:[1,0]
	v_pk_mul_f32 v[2:3], v[4:5], v[0:1] op_sel_hi:[1,0]
	v_pk_mul_f32 v[6:7], v[6:7], v[0:1] op_sel_hi:[1,0]
	v_pk_mul_f32 v[8:9], v[8:9], v[0:1] op_sel_hi:[1,0]
	s_nop 0
	v_cvt_pk_bf16_f32 v0, v8, v9
	v_cvt_pk_bf16_f32 v1, v6, v7
	v_cvt_pk_bf16_f32 v2, v2, v3
	v_cvt_pk_bf16_f32 v3, v10, v11
	v_mov_b32_dpp v180, v184 row_ror:8 row_mask:0xf bank_mask:0xf
	v_mov_b32_dpp v181, v185 row_ror:8 row_mask:0xf bank_mask:0xf
	v_mov_b32_dpp v182, v186 row_ror:8 row_mask:0xf bank_mask:0xf
	v_mov_b32_dpp v183, v187 row_ror:8 row_mask:0xf bank_mask:0xf
	v_lshl_add_u64 v[212:213], v[174:175], 0, v[218:219]
	v_mov_b32_dpp v184, v0 row_ror:8 row_mask:0xf bank_mask:0xc
	v_mov_b32_dpp v185, v1 row_ror:8 row_mask:0xf bank_mask:0xc
	v_mov_b32_dpp v186, v2 row_ror:8 row_mask:0xf bank_mask:0xc
	v_mov_b32_dpp v187, v3 row_ror:8 row_mask:0xf bank_mask:0xc
	v_lshl_add_u64 v[214:215], v[174:175], 0, v[220:221]
	v_cndmask_b32_e32 v0, v180, v0, vcc
	v_cndmask_b32_e32 v1, v181, v1, vcc
	v_cndmask_b32_e32 v2, v182, v2, vcc
	v_cndmask_b32_e32 v3, v183, v3, vcc
	s_nop 0
	global_store_dwordx4 v[212:213], v[184:187], off nt
	global_store_dwordx4 v[214:215], v[0:3], off nt
	s_andn2_b64 vcc, exec, s[38:39]
	s_mov_b64 s[0:1], -1
	s_cbranch_vccnz .LBB0_350

; __device__ __forceinline__ unsigned cvt_pk_bf16(float lo, float hi) { unsigned r; asm volatile("v_cvt_pk_bf16_f32 %0, %1, %2" : "=v"(r) : "v"(lo), "v"(hi)); return r; }
;     __device__ __forceinline__ void operator()(const f32x4 (&acc)[2][2][4][2], const Unit& u, int wr, int wc, int fr, int fq) const {
;     ...
;             const int blk = colt >> 10, g = blk % 3, sec = blk / 3; const int dsh = (g == 0) ? 0 : (g == 1 ? 2 : 4); const int cin = (colt & 1023) + 64 * wc + 8 * fq;
;             f32x4 gn[2][2];
;             const float* gp = (sec == 0) ? qg + g * 64 : kg + g * 64;
; #pragma unroll
;             for (int bj = 0; bj < 2; ++bj)
; #pragma unroll
;                 for (int n = 0; n < 2; ++n) gn[bj][n] = (sec < 2) ? *(const f32x4*)(gp + 32 * bj + 8 * fq + 4 * n) : (f32x4){1.f, 1.f, 1.f, 1.f};
;             const float qsc = (sec == 0) ? 0.125f * 1.4426950408889634f : 1.0f;
; #pragma unroll
;             for (int ai = 0; ai < 2; ++ai)
; #pragma unroll
;                 for (int m = 0; m < 4; ++m) {
;                     const int r = row0 + ai * HALF + m * 16;
;                     const float rs = __builtin_amdgcn_rsqf((float)ss[r] * (1.0f / 1048576.0f) * (1.0f / 1024.0f) + EPS);
;                     f32x4 v[2][2]; float sq = 0.f;
; #pragma unroll
;                     for (int bj = 0; bj < 2; ++bj)
; #pragma unroll
;                         for (int n = 0; n < 2; ++n) { v[bj][n] = acc[ai][bj][m][n] * rs; sq += (v[bj][n][0] * v[bj][n][0] + v[bj][n][1] * v[bj][n][1]) + (v[bj][n][2] * v[bj][n][2] + v[bj][n][3] * v[bj][n][3]); }
;                     sq = x16_sum(sq); sq = x32_sum(sq);
;                     const float r2 = (sec < 2) ? qsc * __builtin_amdgcn_rsqf(sq * (1.0f / 64.0f) + EPS) : 1.0f;
;                     const int bl = r >> 13, t = r & 8191; const int pr = (bl << 13) + ((t & ((1 << dsh) - 1)) << (13 - dsh)) + (t >> dsh);
;                     bf16_t* rowp = O + (size_t)blk * SEC + (size_t)pr * 1024 + cin;
; #pragma unroll
;                     for (int bj = 0; bj < 2; ++bj) { const f32x4 v0 = v[bj][0] * gn[bj][0] * r2, v1 = v[bj][1] * gn[bj][1] * r2;
;                         u32x4 w; w.x = cvt_pk_bf16(v0[0], v0[1]); w.y = cvt_pk_bf16(v0[2], v0[3]); w.z = cvt_pk_bf16(v1[0], v1[1]); w.w = cvt_pk_bf16(v1[2], v1[3]);
;                         *(u32x4*)(rowp + bj * 32) = w; }
.Lv433:
	s_mov_b32 vcc_lo, 0xff00ff00
	s_mov_b32 vcc_hi, 0xff00ff00
	s_nop 1
	v_lshl_add_u64 v[162:163], v[160:161], 3, s[48:49]
	s_cmp_eq_u32 s2, 1
	s_cselect_b32 s34, 2, 4
	s_cmp_lg_u32 s2, 0
	v_cndmask_b32_e64 v171, 1.0, v234, s[0:1]
	s_cselect_b32 s34, s34, 0
	s_sub_i32 s42, 13, s34
	s_and_b32 s43, s69, 0xffffe000
	s_ashr_i32 s89, s88, 31
	s_and_b32 s2, s76, 0x300
	s_lshl_b64 s[0:1], s[88:89], 25
	s_add_u32 s0, s28, s0
	v_or_b32_e32 v172, s2, v169
	s_addc_u32 s1, s29, s1
	s_movk_i32 s2, 0x1fdf
	s_mov_b32 s88, 0x1000
	s_cmp_eq_u32 s34, 0
	s_cselect_b32 s88, 0x4000, s88
	s_cmp_eq_u32 s34, 4
	s_cselect_b32 s88, 0x800000, s88
	s_lshr_b32 s89, 0x8000, s34
	v_mov_b32_e32 v220, s88
	v_mov_b32_e32 v176, s89
	s_mul_i32 s89, s89, 5
	v_mov_b32_e32 v177, 0
	v_sub_u32_e32 v218, 64, v220
	v_mov_b32_e32 v178, s89
	v_mov_b32_e32 v179, 0
	v_cndmask_b32_e64 v219, 0, -1, vcc
	v_cndmask_b32_e64 v218, 0, v218, vcc
	v_cndmask_b32_e64 v220, v220, 64, vcc
	v_mov_b32_e32 v221, 0
	s_waitcnt vmcnt(0)
	s_nop 1
	v_cvt_f32_u32_e32 v165, v193
	v_cvt_f32_u32_e32 v164, v192
	v_fmamk_f32 v164, v165, 0x4f800000, v164
	v_fmamk_f32 v164, v164, 0x30800000, v229
	v_rsq_f32_e32 v112, v164
	s_nop 0
	v_pk_mul_f32 v[144:145], v[144:145], v[112:113] op_sel_hi:[1,0]
	v_pk_mul_f32 v[164:165], v[142:143], v[112:113] op_sel_hi:[1,0]
	v_pk_mul_f32 v[140:141], v[140:141], v[112:113] op_sel_hi:[1,0]
	v_pk_mul_f32 v[142:143], v[138:139], v[112:113] op_sel_hi:[1,0]
	v_pk_mul_f32 v[136:137], v[136:137], v[112:113] op_sel_hi:[1,0]
	v_pk_mul_f32 v[138:139], v[134:135], v[112:113] op_sel_hi:[1,0]
	v_pk_mul_f32 v[132:133], v[132:133], v[112:113] op_sel_hi:[1,0]
	v_pk_mul_f32 v[134:135], v[130:131], v[112:113] op_sel_hi:[1,0]
	v_lshlrev_b32_e32 v131, s42, v160
	v_and_b32_e32 v131, 0x1ffe, v131
	v_and_b32_e32 v112, 0x1fcf, v160
	v_lshrrev_b32_e32 v112, s34, v112
	v_or_b32_e32 v112, s43, v112
	v_add_u32_e32 v166, v112, v131
	v_ashrrev_i32_e32 v167, 31, v166
	v_lshlrev_b64 v[166:167], 11, v[166:167]
	v_lshl_add_u64 v[166:167], s[0:1], 0, v[166:167]
	v_lshlrev_b32_e32 v112, 1, v172
	v_lshl_add_u64 v[166:167], v[166:167], 0, v[112:113]
	v_cvt_pk_bf16_f32 v184, v164, v165
	v_cvt_pk_bf16_f32 v185, v144, v145
	v_cvt_pk_bf16_f32 v186, v142, v143
	v_cvt_pk_bf16_f32 v187, v140, v141
	s_nop 0
	v_cvt_pk_bf16_f32 v208, v138, v139
	v_cvt_pk_bf16_f32 v209, v136, v137
	v_cvt_pk_bf16_f32 v210, v134, v135
	v_cvt_pk_bf16_f32 v211, v132, v133
	v_mov_b32_dpp v180, v184 row_ror:8 row_mask:0xf bank_mask:0xf
	v_mov_b32_dpp v181, v185 row_ror:8 row_mask:0xf bank_mask:0xf
	v_mov_b32_dpp v182, v186 row_ror:8 row_mask:0xf bank_mask:0xf
	v_mov_b32_dpp v183, v187 row_ror:8 row_mask:0xf bank_mask:0xf
	v_lshl_add_u64 v[212:213], v[166:167], 0, v[218:219]
	v_mov_b32_dpp v184, v208 row_ror:8 row_mask:0xf bank_mask:0xc
	v_mov_b32_dpp v185, v209 row_ror:8 row_mask:0xf bank_mask:0xc
	v_mov_b32_dpp v186, v210 row_ror:8 row_mask:0xf bank_mask:0xc
	v_mov_b32_dpp v187, v211 row_ror:8 row_mask:0xf bank_mask:0xc
	v_lshl_add_u64 v[214:215], v[166:167], 0, v[220:221]
	v_cndmask_b32_e32 v208, v180, v208, vcc
	v_cndmask_b32_e32 v209, v181, v209, vcc
	v_cndmask_b32_e32 v210, v182, v210, vcc
	v_cndmask_b32_e32 v211, v183, v211, vcc
	s_nop 0
	global_store_dwordx4 v[212:213], v[184:187], off nt
	global_store_dwordx4 v[214:215], v[208:211], off nt
	v_lshl_add_u64 v[174:175], v[166:167], 0, v[176:177]
	s_nop 1
	v_or_b32_e32 v133, 16, v160
	v_cvt_f32_u32_e32 v131, v195
	v_cvt_f32_u32_e32 v130, v194
	v_fmamk_f32 v130, v131, 0x4f800000, v130
	v_fmamk_f32 v130, v130, 0x30800000, v229
	v_rsq_f32_e32 v132, v130
	s_nop 0
	v_pk_mul_f32 v[128:129], v[128:129], v[132:133] op_sel_hi:[1,0]
	v_pk_mul_f32 v[130:131], v[126:127], v[132:133] op_sel_hi:[1,0]
	v_pk_mul_f32 v[124:125], v[124:125], v[132:133] op_sel_hi:[1,0]
	v_pk_mul_f32 v[126:127], v[122:123], v[132:133] op_sel_hi:[1,0]
	v_pk_mul_f32 v[120:121], v[120:121], v[132:133] op_sel_hi:[1,0]
	v_pk_mul_f32 v[122:123], v[118:119], v[132:133] op_sel_hi:[1,0]
	v_pk_mul_f32 v[116:117], v[116:117], v[132:133] op_sel_hi:[1,0]
	v_pk_mul_f32 v[118:119], v[114:115], v[132:133] op_sel_hi:[1,0]
	s_nop 0
	v_cvt_pk_bf16_f32 v184, v130, v131
	v_cvt_pk_bf16_f32 v185, v128, v129
	v_cvt_pk_bf16_f32 v186, v126, v127
	v_cvt_pk_bf16_f32 v187, v124, v125
	s_movk_i32 s2, 0x1fef
	v_cvt_pk_bf16_f32 v208, v122, v123
	v_cvt_pk_bf16_f32 v209, v120, v121
	v_cvt_pk_bf16_f32 v210, v118, v119
	v_cvt_pk_bf16_f32 v211, v116, v117
	v_mov_b32_dpp v180, v184 row_ror:8 row_mask:0xf bank_mask:0xf
	v_mov_b32_dpp v181, v185 row_ror:8 row_mask:0xf bank_mask:0xf
	v_mov_b32_dpp v182, v186 row_ror:8 row_mask:0xf bank_mask:0xf
	v_mov_b32_dpp v183, v187 row_ror:8 row_mask:0xf bank_mask:0xf
	v_lshl_add_u64 v[212:213], v[174:175], 0, v[218:219]
	v_mov_b32_dpp v184, v208 row_ror:8 row_mask:0xf bank_mask:0xc
	v_mov_b32_dpp v185, v209 row_ror:8 row_mask:0xf bank_mask:0xc
	v_mov_b32_dpp v186, v210 row_ror:8 row_mask:0xf bank_mask:0xc
	v_mov_b32_dpp v187, v211 row_ror:8 row_mask:0xf bank_mask:0xc
	v_lshl_add_u64 v[214:215], v[174:175], 0, v[220:221]
	v_cndmask_b32_e32 v208, v180, v208, vcc
	v_cndmask_b32_e32 v209, v181, v209, vcc
	v_cndmask_b32_e32 v210, v182, v210, vcc
	v_cndmask_b32_e32 v211, v183, v211, vcc
	s_nop 0
	global_store_dwordx4 v[212:213], v[184:187], off nt
	global_store_dwordx4 v[214:215], v[208:211], off nt
	v_lshl_add_u64 v[174:175], v[174:175], 0, v[176:177]
	s_nop 1
	v_or_b32_e32 v117, 32, v160
	v_cvt_f32_u32_e32 v115, v197
	v_cvt_f32_u32_e32 v114, v196
	v_fmamk_f32 v114, v115, 0x4f800000, v114
	v_fmamk_f32 v114, v114, 0x30800000, v229
	v_rsq_f32_e32 v116, v114
	s_nop 0
	v_pk_mul_f32 v[110:111], v[110:111], v[116:117] op_sel_hi:[1,0]
; __device__ __forceinline__ unsigned cvt_pk_bf16(float lo, float hi) { unsigned r; asm volatile("v_cvt_pk_bf16_f32 %0, %1, %2" : "=v"(r) : "v"(lo), "v"(hi)); return r; }
; DI float x16_sum(float x) { const unsigned u = __builtin_bit_cast(unsigned, x); auto r = __builtin_amdgcn_permlane16_swap(u, u, false, false); return __builtin_bit_cast(float, (unsigned)r[0]) + __builtin_bit_cast(float, (unsigned)r[1]); }
; DI float x32_sum(float x) { const unsigned u = __builtin_bit_cast(unsigned, x); auto r = __builtin_amdgcn_permlane32_swap(u, u, false, false); return __builtin_bit_cast(float, (unsigned)r[0]) + __builtin_bit_cast(float, (unsigned)r[1]); }
;     __device__ __forceinline__ void operator()(const f32x4 (&acc)[2][2][4][2], const Unit& u, int wr, int wc, int fr, int fq) const {
;     ...
;                     const int r = row0 + ai * HALF + m * 16;
;                     const float rs = __builtin_amdgcn_rsqf((float)ss[r] * (1.0f / 1048576.0f) * (1.0f / 1024.0f) + EPS);
;                     f32x4 v[2][2]; float sq = 0.f;
; #pragma unroll
;                     for (int bj = 0; bj < 2; ++bj)
; #pragma unroll
;                         for (int n = 0; n < 2; ++n) { v[bj][n] = acc[ai][bj][m][n] * rs; sq += (v[bj][n][0] * v[bj][n][0] + v[bj][n][1] * v[bj][n][1]) + (v[bj][n][2] * v[bj][n][2] + v[bj][n][3] * v[bj][n][3]); }
;                     sq = x16_sum(sq); sq = x32_sum(sq);
;                     const float r2 = (sec < 2) ? qsc * __builtin_amdgcn_rsqf(sq * (1.0f / 64.0f) + EPS) : 1.0f;
;                     const int bl = r >> 13, t = r & 8191; const int pr = (bl << 13) + ((t & ((1 << dsh) - 1)) << (13 - dsh)) + (t >> dsh);
;                     bf16_t* rowp = O + (size_t)blk * SEC + (size_t)pr * 1024 + cin;
; #pragma unroll
;                     for (int bj = 0; bj < 2; ++bj) { const f32x4 v0 = v[bj][0] * gn[bj][0] * r2, v1 = v[bj][1] * gn[bj][1] * r2;
;                         u32x4 w; w.x = cvt_pk_bf16(v0[0], v0[1]); w.y = cvt_pk_bf16(v0[2], v0[3]); w.z = cvt_pk_bf16(v1[0], v1[1]); w.w = cvt_pk_bf16(v1[2], v1[3]);
;                         *(u32x4*)(rowp + bj * 32) = w; }
	v_pk_mul_f32 v[114:115], v[108:109], v[116:117] op_sel_hi:[1,0]
	v_pk_mul_f32 v[106:107], v[106:107], v[116:117] op_sel_hi:[1,0]
	v_pk_mul_f32 v[108:109], v[104:105], v[116:117] op_sel_hi:[1,0]
	v_pk_mul_f32 v[102:103], v[102:103], v[116:117] op_sel_hi:[1,0]
	v_pk_mul_f32 v[104:105], v[100:101], v[116:117] op_sel_hi:[1,0]
	v_pk_mul_f32 v[98:99], v[98:99], v[116:117] op_sel_hi:[1,0]
	v_pk_mul_f32 v[100:101], v[96:97], v[116:117] op_sel_hi:[1,0]
	s_nop 0
	v_cvt_pk_bf16_f32 v184, v114, v115
	v_cvt_pk_bf16_f32 v185, v110, v111
	v_cvt_pk_bf16_f32 v186, v108, v109
	v_cvt_pk_bf16_f32 v187, v106, v107
	s_movk_i32 s2, 0x1fff
	v_cvt_pk_bf16_f32 v208, v104, v105
	v_cvt_pk_bf16_f32 v209, v102, v103
	v_cvt_pk_bf16_f32 v210, v100, v101
	v_cvt_pk_bf16_f32 v211, v98, v99
	v_mov_b32_dpp v180, v184 row_ror:8 row_mask:0xf bank_mask:0xf
	v_mov_b32_dpp v181, v185 row_ror:8 row_mask:0xf bank_mask:0xf
	v_mov_b32_dpp v182, v186 row_ror:8 row_mask:0xf bank_mask:0xf
	v_mov_b32_dpp v183, v187 row_ror:8 row_mask:0xf bank_mask:0xf
	v_lshl_add_u64 v[212:213], v[174:175], 0, v[218:219]
	v_mov_b32_dpp v184, v208 row_ror:8 row_mask:0xf bank_mask:0xc
	v_mov_b32_dpp v185, v209 row_ror:8 row_mask:0xf bank_mask:0xc
	v_mov_b32_dpp v186, v210 row_ror:8 row_mask:0xf bank_mask:0xc
	v_mov_b32_dpp v187, v211 row_ror:8 row_mask:0xf bank_mask:0xc
	v_lshl_add_u64 v[214:215], v[174:175], 0, v[220:221]
	v_cndmask_b32_e32 v208, v180, v208, vcc
	v_cndmask_b32_e32 v209, v181, v209, vcc
	v_cndmask_b32_e32 v210, v182, v210, vcc
	v_cndmask_b32_e32 v211, v183, v211, vcc
	s_nop 0
	global_store_dwordx4 v[212:213], v[184:187], off nt
	global_store_dwordx4 v[214:215], v[208:211], off nt
	v_lshl_add_u64 v[174:175], v[174:175], 0, v[176:177]
	s_nop 1
	v_or_b32_e32 v99, 48, v160
	v_cvt_f32_u32_e32 v97, v199
	v_cvt_f32_u32_e32 v96, v198
	v_fmamk_f32 v96, v97, 0x4f800000, v96
	v_fmamk_f32 v96, v96, 0x30800000, v229
	v_rsq_f32_e32 v98, v96
	s_nop 0
	v_pk_mul_f32 v[78:79], v[78:79], v[98:99] op_sel_hi:[1,0]
	v_pk_mul_f32 v[96:97], v[76:77], v[98:99] op_sel_hi:[1,0]
	v_pk_mul_f32 v[74:75], v[74:75], v[98:99] op_sel_hi:[1,0]
	v_pk_mul_f32 v[76:77], v[72:73], v[98:99] op_sel_hi:[1,0]
	v_pk_mul_f32 v[70:71], v[70:71], v[98:99] op_sel_hi:[1,0]
	v_pk_mul_f32 v[72:73], v[68:69], v[98:99] op_sel_hi:[1,0]
	v_pk_mul_f32 v[66:67], v[66:67], v[98:99] op_sel_hi:[1,0]
	v_pk_mul_f32 v[68:69], v[64:65], v[98:99] op_sel_hi:[1,0]
	s_nop 0
	v_cvt_pk_bf16_f32 v184, v96, v97
	v_cvt_pk_bf16_f32 v185, v78, v79
	v_cvt_pk_bf16_f32 v186, v76, v77
	v_cvt_pk_bf16_f32 v187, v74, v75
	s_nop 0
	v_cvt_pk_bf16_f32 v208, v72, v73
	v_cvt_pk_bf16_f32 v209, v70, v71
	v_cvt_pk_bf16_f32 v210, v68, v69
	v_cvt_pk_bf16_f32 v211, v66, v67
	v_mov_b32_dpp v180, v184 row_ror:8 row_mask:0xf bank_mask:0xf
	v_mov_b32_dpp v181, v185 row_ror:8 row_mask:0xf bank_mask:0xf
	v_mov_b32_dpp v182, v186 row_ror:8 row_mask:0xf bank_mask:0xf
	v_mov_b32_dpp v183, v187 row_ror:8 row_mask:0xf bank_mask:0xf
	v_lshl_add_u64 v[212:213], v[174:175], 0, v[218:219]
	v_mov_b32_dpp v184, v208 row_ror:8 row_mask:0xf bank_mask:0xc
	v_mov_b32_dpp v185, v209 row_ror:8 row_mask:0xf bank_mask:0xc
	v_mov_b32_dpp v186, v210 row_ror:8 row_mask:0xf bank_mask:0xc
	v_mov_b32_dpp v187, v211 row_ror:8 row_mask:0xf bank_mask:0xc
	v_lshl_add_u64 v[214:215], v[174:175], 0, v[220:221]
	v_cndmask_b32_e32 v208, v180, v208, vcc
	v_cndmask_b32_e32 v209, v181, v209, vcc
	v_cndmask_b32_e32 v210, v182, v210, vcc
	v_cndmask_b32_e32 v211, v183, v211, vcc
	s_nop 0
	global_store_dwordx4 v[212:213], v[184:187], off nt
	global_store_dwordx4 v[214:215], v[208:211], off nt
	v_lshl_add_u64 v[174:175], v[174:175], 0, v[178:179]
	s_nop 1
	v_add_u32_e32 v67, 0x80, v160
	v_cvt_f32_u32_e32 v65, v201
	v_cvt_f32_u32_e32 v64, v200
	v_fmamk_f32 v64, v65, 0x4f800000, v64
	v_fmamk_f32 v64, v64, 0x30800000, v229
	v_rsq_f32_e32 v66, v64
	s_nop 0
	v_pk_mul_f32 v[62:63], v[62:63], v[66:67] op_sel_hi:[1,0]
	v_pk_mul_f32 v[64:65], v[60:61], v[66:67] op_sel_hi:[1,0]
	v_pk_mul_f32 v[58:59], v[58:59], v[66:67] op_sel_hi:[1,0]
	v_pk_mul_f32 v[60:61], v[56:57], v[66:67] op_sel_hi:[1,0]
	v_pk_mul_f32 v[54:55], v[54:55], v[66:67] op_sel_hi:[1,0]
	v_pk_mul_f32 v[56:57], v[52:53], v[66:67] op_sel_hi:[1,0]
	v_pk_mul_f32 v[50:51], v[50:51], v[66:67] op_sel_hi:[1,0]
	v_pk_mul_f32 v[52:53], v[48:49], v[66:67] op_sel_hi:[1,0]
	s_nop 0
	v_cvt_pk_bf16_f32 v184, v64, v65
	v_cvt_pk_bf16_f32 v185, v62, v63
	v_cvt_pk_bf16_f32 v186, v60, v61
	v_cvt_pk_bf16_f32 v187, v58, v59
	s_nop 0
	v_cvt_pk_bf16_f32 v208, v56, v57
	v_cvt_pk_bf16_f32 v209, v54, v55
	v_cvt_pk_bf16_f32 v210, v52, v53
	v_cvt_pk_bf16_f32 v211, v50, v51
	v_mov_b32_dpp v180, v184 row_ror:8 row_mask:0xf bank_mask:0xf
	v_mov_b32_dpp v181, v185 row_ror:8 row_mask:0xf bank_mask:0xf
	v_mov_b32_dpp v182, v186 row_ror:8 row_mask:0xf bank_mask:0xf
	v_mov_b32_dpp v183, v187 row_ror:8 row_mask:0xf bank_mask:0xf
	v_lshl_add_u64 v[212:213], v[174:175], 0, v[218:219]
	v_mov_b32_dpp v184, v208 row_ror:8 row_mask:0xf bank_mask:0xc
	v_mov_b32_dpp v185, v209 row_ror:8 row_mask:0xf bank_mask:0xc
	v_mov_b32_dpp v186, v210 row_ror:8 row_mask:0xf bank_mask:0xc
	v_mov_b32_dpp v187, v211 row_ror:8 row_mask:0xf bank_mask:0xc
	v_lshl_add_u64 v[214:215], v[174:175], 0, v[220:221]
	v_cndmask_b32_e32 v208, v180, v208, vcc
	v_cndmask_b32_e32 v209, v181, v209, vcc
	v_cndmask_b32_e32 v210, v182, v210, vcc
	v_cndmask_b32_e32 v211, v183, v211, vcc
	s_nop 0
	global_store_dwordx4 v[212:213], v[184:187], off nt
	global_store_dwordx4 v[214:215], v[208:211], off nt
	v_lshl_add_u64 v[174:175], v[174:175], 0, v[176:177]
	s_nop 1
	v_add_u32_e32 v51, 0x90, v160
	v_cvt_f32_u32_e32 v49, v203
	v_cvt_f32_u32_e32 v48, v202
; __device__ __forceinline__ unsigned cvt_pk_bf16(float lo, float hi) { unsigned r; asm volatile("v_cvt_pk_bf16_f32 %0, %1, %2" : "=v"(r) : "v"(lo), "v"(hi)); return r; }
; DI float x16_sum(float x) { const unsigned u = __builtin_bit_cast(unsigned, x); auto r = __builtin_amdgcn_permlane16_swap(u, u, false, false); return __builtin_bit_cast(float, (unsigned)r[0]) + __builtin_bit_cast(float, (unsigned)r[1]); }
; DI float x32_sum(float x) { const unsigned u = __builtin_bit_cast(unsigned, x); auto r = __builtin_amdgcn_permlane32_swap(u, u, false, false); return __builtin_bit_cast(float, (unsigned)r[0]) + __builtin_bit_cast(float, (unsigned)r[1]); }
;     __device__ __forceinline__ void operator()(const f32x4 (&acc)[2][2][4][2], const Unit& u, int wr, int wc, int fr, int fq) const {
;     ...
;                     const int r = row0 + ai * HALF + m * 16;
;                     const float rs = __builtin_amdgcn_rsqf((float)ss[r] * (1.0f / 1048576.0f) * (1.0f / 1024.0f) + EPS);
;                     f32x4 v[2][2]; float sq = 0.f;
; #pragma unroll
;                     for (int bj = 0; bj < 2; ++bj)
; #pragma unroll
;                         for (int n = 0; n < 2; ++n) { v[bj][n] = acc[ai][bj][m][n] * rs; sq += (v[bj][n][0] * v[bj][n][0] + v[bj][n][1] * v[bj][n][1]) + (v[bj][n][2] * v[bj][n][2] + v[bj][n][3] * v[bj][n][3]); }
;                     sq = x16_sum(sq); sq = x32_sum(sq);
;                     const float r2 = (sec < 2) ? qsc * __builtin_amdgcn_rsqf(sq * (1.0f / 64.0f) + EPS) : 1.0f;
;                     const int bl = r >> 13, t = r & 8191; const int pr = (bl << 13) + ((t & ((1 << dsh) - 1)) << (13 - dsh)) + (t >> dsh);
;                     bf16_t* rowp = O + (size_t)blk * SEC + (size_t)pr * 1024 + cin;
; #pragma unroll
;                     for (int bj = 0; bj < 2; ++bj) { const f32x4 v0 = v[bj][0] * gn[bj][0] * r2, v1 = v[bj][1] * gn[bj][1] * r2;
;                         u32x4 w; w.x = cvt_pk_bf16(v0[0], v0[1]); w.y = cvt_pk_bf16(v0[2], v0[3]); w.z = cvt_pk_bf16(v1[0], v1[1]); w.w = cvt_pk_bf16(v1[2], v1[3]);
;                         *(u32x4*)(rowp + bj * 32) = w; }
	v_fmamk_f32 v48, v49, 0x4f800000, v48
	v_fmamk_f32 v48, v48, 0x30800000, v229
	v_rsq_f32_e32 v50, v48
	s_nop 0
	v_pk_mul_f32 v[46:47], v[46:47], v[50:51] op_sel_hi:[1,0]
	v_pk_mul_f32 v[48:49], v[44:45], v[50:51] op_sel_hi:[1,0]
	v_pk_mul_f32 v[42:43], v[42:43], v[50:51] op_sel_hi:[1,0]
	v_pk_mul_f32 v[44:45], v[40:41], v[50:51] op_sel_hi:[1,0]
	v_pk_mul_f32 v[38:39], v[38:39], v[50:51] op_sel_hi:[1,0]
	v_pk_mul_f32 v[40:41], v[36:37], v[50:51] op_sel_hi:[1,0]
	v_pk_mul_f32 v[34:35], v[34:35], v[50:51] op_sel_hi:[1,0]
	v_pk_mul_f32 v[36:37], v[32:33], v[50:51] op_sel_hi:[1,0]
	s_nop 0
	v_cvt_pk_bf16_f32 v184, v48, v49
	v_cvt_pk_bf16_f32 v185, v46, v47
	v_cvt_pk_bf16_f32 v186, v44, v45
	v_cvt_pk_bf16_f32 v187, v42, v43
	s_nop 0
	v_cvt_pk_bf16_f32 v208, v40, v41
	v_cvt_pk_bf16_f32 v209, v38, v39
	v_cvt_pk_bf16_f32 v210, v36, v37
	v_cvt_pk_bf16_f32 v211, v34, v35
	v_mov_b32_dpp v180, v184 row_ror:8 row_mask:0xf bank_mask:0xf
	v_mov_b32_dpp v181, v185 row_ror:8 row_mask:0xf bank_mask:0xf
	v_mov_b32_dpp v182, v186 row_ror:8 row_mask:0xf bank_mask:0xf
	v_mov_b32_dpp v183, v187 row_ror:8 row_mask:0xf bank_mask:0xf
	v_lshl_add_u64 v[212:213], v[174:175], 0, v[218:219]
	v_mov_b32_dpp v184, v208 row_ror:8 row_mask:0xf bank_mask:0xc
	v_mov_b32_dpp v185, v209 row_ror:8 row_mask:0xf bank_mask:0xc
	v_mov_b32_dpp v186, v210 row_ror:8 row_mask:0xf bank_mask:0xc
	v_mov_b32_dpp v187, v211 row_ror:8 row_mask:0xf bank_mask:0xc
	v_lshl_add_u64 v[214:215], v[174:175], 0, v[220:221]
	v_cndmask_b32_e32 v208, v180, v208, vcc
	v_cndmask_b32_e32 v209, v181, v209, vcc
	v_cndmask_b32_e32 v210, v182, v210, vcc
	v_cndmask_b32_e32 v211, v183, v211, vcc
	s_nop 0
	global_store_dwordx4 v[212:213], v[184:187], off nt
	global_store_dwordx4 v[214:215], v[208:211], off nt
	v_lshl_add_u64 v[174:175], v[174:175], 0, v[176:177]
	s_nop 1
	v_add_u32_e32 v35, 0xa0, v160
	v_cvt_f32_u32_e32 v33, v205
	v_cvt_f32_u32_e32 v32, v204
	v_fmamk_f32 v32, v33, 0x4f800000, v32
	v_fmamk_f32 v32, v32, 0x30800000, v229
	v_rsq_f32_e32 v34, v32
	s_nop 0
	v_pk_mul_f32 v[30:31], v[30:31], v[34:35] op_sel_hi:[1,0]
	v_pk_mul_f32 v[32:33], v[28:29], v[34:35] op_sel_hi:[1,0]
	v_pk_mul_f32 v[26:27], v[26:27], v[34:35] op_sel_hi:[1,0]
	v_pk_mul_f32 v[28:29], v[24:25], v[34:35] op_sel_hi:[1,0]
	v_pk_mul_f32 v[22:23], v[22:23], v[34:35] op_sel_hi:[1,0]
	v_pk_mul_f32 v[24:25], v[20:21], v[34:35] op_sel_hi:[1,0]
	v_pk_mul_f32 v[18:19], v[18:19], v[34:35] op_sel_hi:[1,0]
	v_pk_mul_f32 v[20:21], v[16:17], v[34:35] op_sel_hi:[1,0]
	s_nop 0
	v_cvt_pk_bf16_f32 v184, v32, v33
	v_cvt_pk_bf16_f32 v185, v30, v31
	v_cvt_pk_bf16_f32 v186, v28, v29
	v_cvt_pk_bf16_f32 v187, v26, v27
	s_nop 0
	v_cvt_pk_bf16_f32 v208, v24, v25
	v_cvt_pk_bf16_f32 v209, v22, v23
	v_cvt_pk_bf16_f32 v210, v20, v21
	v_cvt_pk_bf16_f32 v211, v18, v19
	v_mov_b32_dpp v180, v184 row_ror:8 row_mask:0xf bank_mask:0xf
	v_mov_b32_dpp v181, v185 row_ror:8 row_mask:0xf bank_mask:0xf
	v_mov_b32_dpp v182, v186 row_ror:8 row_mask:0xf bank_mask:0xf
	v_mov_b32_dpp v183, v187 row_ror:8 row_mask:0xf bank_mask:0xf
	v_lshl_add_u64 v[212:213], v[174:175], 0, v[218:219]
	v_mov_b32_dpp v184, v208 row_ror:8 row_mask:0xf bank_mask:0xc
	v_mov_b32_dpp v185, v209 row_ror:8 row_mask:0xf bank_mask:0xc
	v_mov_b32_dpp v186, v210 row_ror:8 row_mask:0xf bank_mask:0xc
	v_mov_b32_dpp v187, v211 row_ror:8 row_mask:0xf bank_mask:0xc
	v_lshl_add_u64 v[214:215], v[174:175], 0, v[220:221]
	v_cndmask_b32_e32 v208, v180, v208, vcc
	v_cndmask_b32_e32 v209, v181, v209, vcc
	v_cndmask_b32_e32 v210, v182, v210, vcc
	v_cndmask_b32_e32 v211, v183, v211, vcc
	s_nop 0
	global_store_dwordx4 v[212:213], v[184:187], off nt
	global_store_dwordx4 v[214:215], v[208:211], off nt
	v_lshl_add_u64 v[174:175], v[174:175], 0, v[176:177]
	s_nop 1
	v_add_u32_e32 v19, 0xb0, v160
	v_cvt_f32_u32_e32 v17, v207
	v_cvt_f32_u32_e32 v16, v206
	v_fmamk_f32 v16, v17, 0x4f800000, v16
	v_fmamk_f32 v16, v16, 0x30800000, v229
	v_rsq_f32_e32 v18, v16
	s_nop 0
	v_pk_mul_f32 v[14:15], v[14:15], v[18:19] op_sel_hi:[1,0]
	v_pk_mul_f32 v[16:17], v[12:13], v[18:19] op_sel_hi:[1,0]
	v_pk_mul_f32 v[10:11], v[10:11], v[18:19] op_sel_hi:[1,0]
	v_pk_mul_f32 v[12:13], v[8:9], v[18:19] op_sel_hi:[1,0]
	v_pk_mul_f32 v[6:7], v[6:7], v[18:19] op_sel_hi:[1,0]
	v_pk_mul_f32 v[8:9], v[4:5], v[18:19] op_sel_hi:[1,0]
	v_pk_mul_f32 v[2:3], v[2:3], v[18:19] op_sel_hi:[1,0]
	v_pk_mul_f32 v[4:5], v[0:1], v[18:19] op_sel_hi:[1,0]
	s_nop 0
	v_cvt_pk_bf16_f32 v184, v16, v17
	v_cvt_pk_bf16_f32 v185, v14, v15
	v_cvt_pk_bf16_f32 v186, v12, v13
	v_cvt_pk_bf16_f32 v187, v10, v11
	s_nop 0
	v_cvt_pk_bf16_f32 v208, v8, v9
	v_cvt_pk_bf16_f32 v209, v6, v7
	v_cvt_pk_bf16_f32 v210, v4, v5
	v_cvt_pk_bf16_f32 v211, v2, v3
	v_mov_b32_dpp v180, v184 row_ror:8 row_mask:0xf bank_mask:0xf
	v_mov_b32_dpp v181, v185 row_ror:8 row_mask:0xf bank_mask:0xf
	v_mov_b32_dpp v182, v186 row_ror:8 row_mask:0xf bank_mask:0xf
	v_mov_b32_dpp v183, v187 row_ror:8 row_mask:0xf bank_mask:0xf
	v_lshl_add_u64 v[212:213], v[174:175], 0, v[218:219]
	v_mov_b32_dpp v184, v208 row_ror:8 row_mask:0xf bank_mask:0xc
	v_mov_b32_dpp v185, v209 row_ror:8 row_mask:0xf bank_mask:0xc
	v_mov_b32_dpp v186, v210 row_ror:8 row_mask:0xf bank_mask:0xc
	v_mov_b32_dpp v187, v211 row_ror:8 row_mask:0xf bank_mask:0xc
	v_lshl_add_u64 v[214:215], v[174:175], 0, v[220:221]
	v_cndmask_b32_e32 v208, v180, v208, vcc
	v_cndmask_b32_e32 v209, v181, v209, vcc
	v_cndmask_b32_e32 v210, v182, v210, vcc
	v_cndmask_b32_e32 v211, v183, v211, vcc
	s_nop 0
	global_store_dwordx4 v[212:213], v[184:187], off nt
	global_store_dwordx4 v[214:215], v[208:211], off nt
	s_andn2_b64 vcc, exec, s[38:39]
	s_mov_b64 s[0:1], -1
	s_cbranch_vccnz .LBB0_350
	s_branch .LBB0_434
